# GLA output phase: premature full VMEM drain moved above the phase's first load so all phase loads issue at once
# baseline (speedup 1.0000x reference)
.LBB0_465:
	s_cmp_lt_i32 s60, 8
	s_cselect_b64 s[0:1], -1, 0
	s_cmp_gt_i32 s61, 7
	s_cselect_b64 s[2:3], -1, 0
	s_and_b64 s[0:1], s[0:1], s[2:3]
	s_andn2_b64 vcc, exec, s[0:1]
	s_cbranch_vccnz .LBB0_512
	s_cmpk_gt_i32 s20, 0xff
	s_cbranch_scc1 .LBB0_476
	s_ashr_i32 s21, s20, 31
	s_lshl_b32 s4, s20, 6
	s_lshl_b64 s[0:1], s[20:21], 12
	s_add_u32 s0, s58, s0
	s_addc_u32 s1, s59, s1
	v_lshlrev_b32_e32 v78, 3, v0
	v_mov_b32_e32 v79, 0
	v_lshl_add_u64 v[2:3], s[0:1], 0, v[78:79]
	v_add_co_u32_e32 v2, vcc, 0x200000, v2
	v_and_b32_e32 v161, 0xff, v0
	s_nop 0
	v_addc_co_u32_e32 v3, vcc, 0, v3, vcc
	v_lshlrev_b32_e32 v150, 2, v161
	v_mov_b32_e32 v151, v79
	s_waitcnt vmcnt(0)
	global_load_dwordx2 v[164:165], v[2:3], off
	v_lshl_add_u64 v[2:3], s[40:41], 0, v[150:151]
	s_movk_i32 s0, 0x1000
	s_nop 0
	v_add_co_u32_e32 v4, vcc, s0, v2
	s_movk_i32 s0, 0x2000
	s_nop 0
	v_addc_co_u32_e32 v5, vcc, 0, v3, vcc
	v_add_co_u32_e32 v6, vcc, s0, v2
	v_lshlrev_b32_e32 v187, 2, v0
	s_nop 0
	v_addc_co_u32_e32 v7, vcc, 0, v3, vcc
	s_movk_i32 s0, 0x3000
	v_or_b32_e32 v8, 0xc00, v187
	v_add_co_u32_e32 v2, vcc, s0, v2
	s_add_u32 s0, s58, 0x8c00000
	v_or_b32_e32 v9, 0x1c00, v187
	v_or_b32_e32 v10, 0x2c00, v187
	v_addc_co_u32_e32 v3, vcc, 0, v3, vcc
	global_load_dword v142, v8, s[40:41]
	global_load_dword v147, v[4:5], off offset:1024
	global_load_dword v145, v[4:5], off offset:2048
	global_load_dword v143, v9, s[40:41]
	global_load_dword v134, v10, s[40:41]
	global_load_dword v139, v[2:3], off
	global_load_dword v141, v[2:3], off offset:1024
	global_load_dword v137, v[2:3], off offset:2048
	v_or_b32_e32 v2, 0x3c00, v187
	s_addc_u32 s1, s59, 0
	v_lshrrev_b32_e32 v160, 5, v0
	s_movk_i32 s12, 0xc00
	global_load_dword v135, v2, s[40:41]
	global_load_dword v148, v150, s[40:41]
	global_load_dword v146, v150, s[40:41] offset:1024
	global_load_dword v144, v150, s[40:41] offset:2048
	global_load_dword v149, v[6:7], off offset:-4096
	global_load_dword v138, v[6:7], off
	global_load_dword v140, v[6:7], off offset:1024
	global_load_dword v136, v[6:7], off offset:2048
	global_load_dword v162, v150, s[42:43]
	v_or_b32_e32 v2, s4, v160
	v_mov_b64_e32 v[18:19], s[0:1]
	v_lshlrev_b32_e32 v6, 4, v0
	v_mad_i64_i32 v[2:3], s[2:3], v2, s12, v[18:19]
	v_and_b32_e32 v4, 0x1f0, v6
	v_mov_b32_e32 v5, v79
	v_or_b32_e32 v7, 0x200, v0
	v_lshl_add_u64 v[2:3], v[2:3], 0, v[4:5]
	v_lshrrev_b32_e32 v159, 5, v7
	global_load_dwordx4 v[74:77], v[2:3], off
	global_load_dwordx4 v[70:73], v[2:3], off offset:512
	v_or_b32_e32 v2, s4, v159
	v_mad_i64_i32 v[2:3], s[2:3], v2, s12, v[18:19]
	v_or_b32_e32 v20, 0x400, v0
	v_lshl_add_u64 v[2:3], v[2:3], 0, v[4:5]
	v_lshrrev_b32_e32 v158, 5, v20
	global_load_dwordx4 v[66:69], v[2:3], off
	global_load_dwordx4 v[62:65], v[2:3], off offset:512
	v_or_b32_e32 v2, s4, v158
	v_mad_i64_i32 v[2:3], s[2:3], v2, s12, v[18:19]
	v_or_b32_e32 v22, 0x600, v0
	v_lshl_add_u64 v[2:3], v[2:3], 0, v[4:5]
	v_lshrrev_b32_e32 v151, 5, v22
	global_load_dwordx4 v[58:61], v[2:3], off
	global_load_dwordx4 v[54:57], v[2:3], off offset:512
	v_or_b32_e32 v2, s4, v151
	v_mad_i64_i32 v[2:3], s[2:3], v2, s12, v[18:19]
	v_lshrrev_b32_e32 v152, 6, v0
	v_lshl_add_u64 v[2:3], v[2:3], 0, v[4:5]
	v_or_b32_e32 v24, s4, v152
	global_load_dwordx4 v[50:53], v[2:3], off
	global_load_dwordx4 v[10:13], v[2:3], off offset:512
	v_mad_i64_i32 v[2:3], s[2:3], v24, s12, v[18:19]
	v_and_b32_e32 v80, 0x3f0, v6
	v_mov_b32_e32 v81, v79
	v_lshrrev_b32_e32 v153, 6, v7
	v_lshl_add_u64 v[14:15], v[2:3], 0, v[80:81]
	v_or_b32_e32 v2, s4, v153
	v_mad_i64_i32 v[2:3], s[2:3], v2, s12, v[18:19]
	v_lshrrev_b32_e32 v154, 6, v20
	v_lshl_add_u64 v[16:17], v[2:3], 0, v[80:81]
	global_load_dwordx4 v[6:9], v[14:15], off offset:1024
	global_load_dwordx4 v[2:5], v[16:17], off offset:1024
	v_or_b32_e32 v14, s4, v154
	v_mad_i64_i32 v[14:15], s[2:3], v14, s12, v[18:19]
	v_lshrrev_b32_e32 v155, 6, v22
	v_lshl_add_u64 v[20:21], v[14:15], 0, v[80:81]
	v_or_b32_e32 v14, s4, v155
	v_mad_i64_i32 v[14:15], s[2:3], v14, s12, v[18:19]
	v_lshl_add_u64 v[22:23], v[14:15], 0, v[80:81]
	global_load_dwordx4 v[30:33], v[20:21], off offset:1024
	global_load_dwordx4 v[14:17], v[22:23], off offset:1024
	v_or_b32_e32 v22, 0xa00, v0
	v_lshrrev_b32_e32 v156, 6, v22
	v_or_b32_e32 v20, 32, v24
	v_or_b32_e32 v22, s4, v156
	v_mad_i64_i32 v[20:21], s[2:3], v20, s12, v[18:19]
	v_mad_i64_i32 v[22:23], s[2:3], v22, s12, v[18:19]
	v_lshl_add_u64 v[20:21], v[20:21], 0, v[80:81]
	v_lshl_add_u64 v[22:23], v[22:23], 0, v[80:81]
	global_load_dwordx4 v[38:41], v[20:21], off offset:1024
	global_load_dwordx4 v[34:37], v[22:23], off offset:1024
	v_or_b32_e32 v22, 0xe00, v0
	v_lshrrev_b32_e32 v157, 6, v22
	v_or_b32_e32 v20, 48, v24
	v_or_b32_e32 v22, s4, v157
	v_mad_i64_i32 v[20:21], s[2:3], v20, s12, v[18:19]
	v_mad_i64_i32 v[18:19], s[2:3], v22, s12, v[18:19]
	v_readlane_b32 s2, v254, 21
	s_lshr_b32 s2, s2, 7
	s_lshl_b32 s3, s20, 2
	s_add_i32 s2, s3, s2
	s_ashr_i32 s3, s2, 31
	s_lshl_b64 s[2:3], s[2:3], 14
	v_lshrrev_b32_e32 v166, 5, v1
	s_add_u32 s2, s58, s2
	s_addc_u32 s3, s59, s3
	v_lshlrev_b32_e32 v182, 4, v166
	v_mov_b32_e32 v183, v79
	v_lshl_add_u64 v[82:83], s[2:3], 0, v[182:183]
	s_mov_b64 s[2:3], 0xe400000
	v_and_b32_e32 v185, 31, v0
	v_lshl_add_u64 v[26:27], v[82:83], 0, s[2:3]
	s_mov_b64 s[2:3], 0xe400020
	v_lshlrev_b32_e32 v28, 7, v185
	v_lshl_add_u64 v[94:95], v[82:83], 0, s[2:3]
	s_mov_b64 s[2:3], 0xe400040
	v_mov_b32_e32 v29, v79
	v_or_b32_e32 v114, 0x1000, v28
	v_mov_b32_e32 v115, v79
	v_or_b32_e32 v116, 0x2000, v28
	v_mov_b32_e32 v117, v79
	v_or_b32_e32 v168, 0x3000, v28
	v_mov_b32_e32 v169, v79
	v_lshl_add_u64 v[118:119], v[82:83], 0, s[2:3]
	s_mov_b64 s[2:3], 0xe400060
	v_lshl_add_u64 v[20:21], v[20:21], 0, v[80:81]
	v_lshl_add_u64 v[18:19], v[18:19], 0, v[80:81]
	v_lshl_add_u64 v[84:85], v[26:27], 0, v[28:29]
	v_lshl_add_u64 v[86:87], v[26:27], 0, v[114:115]
	v_lshl_add_u64 v[88:89], v[26:27], 0, v[116:117]
	v_lshl_add_u64 v[90:91], v[26:27], 0, v[168:169]
	v_lshl_add_u64 v[92:93], v[94:95], 0, v[114:115]
	v_lshl_add_u64 v[96:97], v[94:95], 0, v[116:117]
	v_lshl_add_u64 v[94:95], v[94:95], 0, v[168:169]
	v_lshl_add_u64 v[106:107], v[118:119], 0, v[114:115]
	v_lshl_add_u64 v[108:109], v[118:119], 0, v[116:117]
	v_lshl_add_u64 v[82:83], v[82:83], 0, s[2:3]
	global_load_dwordx4 v[46:49], v[20:21], off offset:1024
	global_load_dwordx4 v[42:45], v[18:19], off offset:1024
	s_nop 0
	global_load_dwordx4 v[18:21], v[86:87], off
	global_load_dwordx4 v[22:25], v[88:89], off
	global_load_dwordx4 v[26:29], v[84:85], off
	s_nop 0
	global_load_dwordx4 v[86:89], v[84:85], off offset:32
	global_load_dwordx4 v[102:105], v[90:91], off
	s_nop 0
	global_load_dwordx4 v[90:93], v[92:93], off
	s_nop 0
	global_load_dwordx4 v[98:101], v[96:97], off
	s_nop 0
	global_load_dwordx4 v[94:97], v[94:95], off
	s_nop 0
	global_load_dwordx4 v[110:113], v[106:107], off
	s_nop 0
	global_load_dwordx4 v[106:109], v[108:109], off
	v_lshl_add_u64 v[122:123], v[118:119], 0, v[168:169]
	global_load_dwordx4 v[130:133], v[84:85], off offset:64
	global_load_dwordx4 v[118:121], v[84:85], off offset:96
	v_lshl_add_u64 v[84:85], v[82:83], 0, v[114:115]
	global_load_dwordx4 v[126:129], v[122:123], off
	s_nop 0
	global_load_dwordx4 v[122:125], v[84:85], off
	v_lshl_add_u64 v[84:85], v[82:83], 0, v[116:117]
	v_lshl_add_u64 v[82:83], v[82:83], 0, v[168:169]
	global_load_dwordx4 v[114:117], v[84:85], off
	s_nop 0
	global_load_dwordx4 v[82:85], v[82:83], off
	s_add_i32 s2, 0, 0x23000
	v_lshrrev_b32_e32 v81, 3, v0
	v_add_u32_e32 v78, s2, v78
	v_and_b32_e32 v163, 32, v81
	s_waitcnt vmcnt(49)
	ds_write_b64 v78, v[164:165]
	v_lshl_add_u32 v78, v163, 6, s2
	s_waitcnt lgkmcnt(0)
	s_barrier
	ds_read_b128 v[168:171], v78
	ds_read_b128 v[172:175], v78 offset:16
	ds_read_b128 v[176:179], v78 offset:32
	ds_read_b128 v[188:191], v78 offset:48
	v_or_b32_e32 v167, 1, v163
	s_waitcnt lgkmcnt(3)
	v_mov_b32_e32 v164, v168
	s_waitcnt lgkmcnt(2)
	v_mov_b32_e32 v165, v172
	v_mov_b32_e32 v172, v169
	s_waitcnt vmcnt(38)
	v_pk_mul_f32 v[168:169], v[146:147], v[172:173]
	s_mov_b32 s3, 0xbd800000
	s_waitcnt vmcnt(36)
	v_pk_fma_f32 v[164:165], v[148:149], v[164:165], v[168:169]
	v_mov_b32_e32 v168, v170
	v_mov_b32_e32 v169, v174
	v_pk_fma_f32 v[164:165], v[144:145], v[168:169], v[164:165]
	v_mov_b32_e32 v174, v171
	v_pk_fma_f32 v[164:165], v[142:143], v[174:175], v[164:165]
	v_or_b32_e32 v180, 2, v163
	s_waitcnt vmcnt(32)
	v_add_f32_e32 v78, v162, v164
	v_add_f32_e32 v78, v78, v165
	s_waitcnt lgkmcnt(0)
	v_mov_b32_e32 v165, v188
	v_mov_b32_e32 v188, v177
	v_mov_b32_e32 v164, v176
	v_pk_mul_f32 v[168:169], v[140:141], v[188:189]
	v_or_b32_e32 v81, 31, v81
	v_pk_fma_f32 v[164:165], v[138:139], v[164:165], v[168:169]
	v_mov_b32_e32 v168, v178
	v_mov_b32_e32 v169, v190
	v_pk_fma_f32 v[164:165], v[136:137], v[168:169], v[164:165]
	v_mov_b32_e32 v190, v179
	v_pk_fma_f32 v[164:165], v[134:135], v[190:191], v[164:165]
	s_nop 0
	v_add_f32_e32 v78, v78, v164
	v_add_f32_e32 v78, v78, v165
	v_max_f32_e32 v78, 0xc2a00000, v78
	v_mul_f32_e32 v78, 0xbfb8aa3b, v78
	v_exp_f32_e32 v78, v78
	s_nop 0
	v_add_f32_e32 v78, 1.0, v78
	v_log_f32_e32 v164, v78
	v_add_u32_e32 v78, 0, v150
	v_mul_f32_e32 v150, 0x3f317218, v164
	v_lshl_add_u32 v164, v167, 6, s2
	ds_read_b128 v[168:171], v164
	ds_read_b128 v[172:175], v164 offset:16
	ds_read_b128 v[176:179], v164 offset:32
	ds_read_b128 v[188:191], v164 offset:48
	v_fma_f32 v150, v150, s3, 0
	s_waitcnt lgkmcnt(3)
	v_mov_b32_e32 v164, v168
	s_waitcnt lgkmcnt(2)
	v_mov_b32_e32 v165, v172
	v_mov_b32_e32 v172, v169
	v_pk_mul_f32 v[168:169], v[146:147], v[172:173]
	s_nop 0
	v_pk_fma_f32 v[164:165], v[148:149], v[164:165], v[168:169]
	v_mov_b32_e32 v168, v170
	v_mov_b32_e32 v169, v174
	v_pk_fma_f32 v[164:165], v[144:145], v[168:169], v[164:165]
	v_mov_b32_e32 v174, v171
	v_pk_fma_f32 v[164:165], v[142:143], v[174:175], v[164:165]
	s_nop 0
	v_add_f32_e32 v164, v162, v164
	v_add_f32_e32 v170, v164, v165
	s_waitcnt lgkmcnt(0)
	v_mov_b32_e32 v165, v188
	v_mov_b32_e32 v188, v177
	v_mov_b32_e32 v164, v176
	v_pk_mul_f32 v[168:169], v[140:141], v[188:189]
	s_nop 0
	v_pk_fma_f32 v[164:165], v[138:139], v[164:165], v[168:169]
	v_mov_b32_e32 v168, v178
	v_mov_b32_e32 v169, v190
	v_pk_fma_f32 v[164:165], v[136:137], v[168:169], v[164:165]
	v_mov_b32_e32 v190, v179
	v_pk_fma_f32 v[164:165], v[134:135], v[190:191], v[164:165]
	s_nop 0
	v_add_f32_e32 v164, v170, v164
	v_add_f32_e32 v164, v164, v165
	v_max_f32_e32 v164, 0xc2a00000, v164
	v_mul_f32_e32 v164, 0xbfb8aa3b, v164
	v_exp_f32_e32 v164, v164
	v_lshl_add_u32 v165, v163, 10, v78
	ds_write_b32 v165, v150
	v_lshl_add_u32 v165, v180, 6, s2
	ds_read_b128 v[168:171], v165
	ds_read_b128 v[172:175], v165 offset:16
	v_add_f32_e32 v164, 1.0, v164
	v_log_f32_e32 v164, v164
	ds_read_b128 v[176:179], v165 offset:32
	ds_read_b128 v[188:191], v165 offset:48
	s_waitcnt lgkmcnt(2)
	v_mov_b32_e32 v165, v172
	v_mov_b32_e32 v172, v169
	v_mul_f32_e32 v181, 0x3f317218, v164
	v_mov_b32_e32 v164, v168
	v_pk_mul_f32 v[168:169], v[146:147], v[172:173]
	v_fmac_f32_e32 v150, 0xbd800000, v181
	v_pk_fma_f32 v[164:165], v[148:149], v[164:165], v[168:169]
	v_mov_b32_e32 v168, v170
	v_mov_b32_e32 v169, v174
	v_pk_fma_f32 v[164:165], v[144:145], v[168:169], v[164:165]
	v_mov_b32_e32 v174, v171
	v_pk_fma_f32 v[164:165], v[142:143], v[174:175], v[164:165]
	s_nop 0
	v_add_f32_e32 v164, v162, v164
	v_add_f32_e32 v170, v164, v165
	s_waitcnt lgkmcnt(0)
	v_mov_b32_e32 v165, v188
	v_mov_b32_e32 v188, v177
	v_mov_b32_e32 v164, v176
	v_pk_mul_f32 v[168:169], v[140:141], v[188:189]
	s_nop 0
	v_pk_fma_f32 v[164:165], v[138:139], v[164:165], v[168:169]
	v_mov_b32_e32 v168, v178
	v_mov_b32_e32 v169, v190
	v_pk_fma_f32 v[164:165], v[136:137], v[168:169], v[164:165]
	v_mov_b32_e32 v190, v179
	v_pk_fma_f32 v[164:165], v[134:135], v[190:191], v[164:165]
	s_nop 0
	v_add_f32_e32 v164, v170, v164
	v_add_f32_e32 v164, v164, v165
	v_max_f32_e32 v164, 0xc2a00000, v164
	v_mul_f32_e32 v164, 0xbfb8aa3b, v164
	v_exp_f32_e32 v164, v164
	v_lshl_add_u32 v165, v167, 10, v78
	v_or_b32_e32 v167, 3, v163
	ds_write_b32 v165, v150
	v_lshl_add_u32 v165, v167, 6, s2
	ds_read_b128 v[168:171], v165
	ds_read_b128 v[172:175], v165 offset:16
	v_add_f32_e32 v164, 1.0, v164
	v_log_f32_e32 v164, v164
	ds_read_b128 v[176:179], v165 offset:32
	ds_read_b128 v[188:191], v165 offset:48
	s_waitcnt lgkmcnt(2)
	v_mov_b32_e32 v165, v172
	v_mov_b32_e32 v172, v169
	v_mul_f32_e32 v181, 0x3f317218, v164
	v_mov_b32_e32 v164, v168
	v_pk_mul_f32 v[168:169], v[146:147], v[172:173]
	v_fmac_f32_e32 v150, 0xbd800000, v181
	v_pk_fma_f32 v[164:165], v[148:149], v[164:165], v[168:169]
	v_mov_b32_e32 v168, v170
	v_mov_b32_e32 v169, v174
	v_pk_fma_f32 v[164:165], v[144:145], v[168:169], v[164:165]
	v_mov_b32_e32 v174, v171
	v_pk_fma_f32 v[164:165], v[142:143], v[174:175], v[164:165]
	s_nop 0
	v_add_f32_e32 v164, v162, v164
	v_add_f32_e32 v170, v164, v165
	s_waitcnt lgkmcnt(0)
	v_mov_b32_e32 v165, v188
	v_mov_b32_e32 v188, v177
	v_mov_b32_e32 v164, v176
	v_pk_mul_f32 v[168:169], v[140:141], v[188:189]
	s_nop 0
	v_pk_fma_f32 v[164:165], v[138:139], v[164:165], v[168:169]
	v_mov_b32_e32 v168, v178
	v_mov_b32_e32 v169, v190
	v_pk_fma_f32 v[164:165], v[136:137], v[168:169], v[164:165]
	v_mov_b32_e32 v190, v179
	v_pk_fma_f32 v[164:165], v[134:135], v[190:191], v[164:165]
	s_nop 0
	v_add_f32_e32 v164, v170, v164
	v_add_f32_e32 v164, v164, v165
	v_max_f32_e32 v164, 0xc2a00000, v164
	v_mul_f32_e32 v164, 0xbfb8aa3b, v164
	v_exp_f32_e32 v164, v164
	v_lshl_add_u32 v165, v180, 10, v78
	v_or_b32_e32 v180, 4, v163
	ds_write_b32 v165, v150
	v_lshl_add_u32 v165, v180, 6, s2
	ds_read_b128 v[168:171], v165
	ds_read_b128 v[172:175], v165 offset:16
	v_add_f32_e32 v164, 1.0, v164
	v_log_f32_e32 v164, v164
	ds_read_b128 v[176:179], v165 offset:32
	ds_read_b128 v[188:191], v165 offset:48
	s_waitcnt lgkmcnt(2)
	v_mov_b32_e32 v165, v172
	v_mov_b32_e32 v172, v169
	v_mul_f32_e32 v181, 0x3f317218, v164
	v_mov_b32_e32 v164, v168
	v_pk_mul_f32 v[168:169], v[146:147], v[172:173]
	v_fmac_f32_e32 v150, 0xbd800000, v181
	v_pk_fma_f32 v[164:165], v[148:149], v[164:165], v[168:169]
	v_mov_b32_e32 v168, v170
	v_mov_b32_e32 v169, v174
	v_pk_fma_f32 v[164:165], v[144:145], v[168:169], v[164:165]
	v_mov_b32_e32 v174, v171
	v_pk_fma_f32 v[164:165], v[142:143], v[174:175], v[164:165]
	s_nop 0
	v_add_f32_e32 v164, v162, v164
	v_add_f32_e32 v170, v164, v165
	s_waitcnt lgkmcnt(0)
	v_mov_b32_e32 v165, v188
	v_mov_b32_e32 v188, v177
	v_mov_b32_e32 v164, v176
	v_pk_mul_f32 v[168:169], v[140:141], v[188:189]
	s_nop 0
	v_pk_fma_f32 v[164:165], v[138:139], v[164:165], v[168:169]
	v_mov_b32_e32 v168, v178
	v_mov_b32_e32 v169, v190
	v_pk_fma_f32 v[164:165], v[136:137], v[168:169], v[164:165]
	v_mov_b32_e32 v190, v179
	v_pk_fma_f32 v[164:165], v[134:135], v[190:191], v[164:165]
	s_nop 0
	v_add_f32_e32 v164, v170, v164
	v_add_f32_e32 v164, v164, v165
	v_max_f32_e32 v164, 0xc2a00000, v164
	v_mul_f32_e32 v164, 0xbfb8aa3b, v164
	v_exp_f32_e32 v164, v164
	v_lshl_add_u32 v165, v167, 10, v78
	v_or_b32_e32 v167, 5, v163
	ds_write_b32 v165, v150
	v_lshl_add_u32 v165, v167, 6, s2
	ds_read_b128 v[168:171], v165
	ds_read_b128 v[172:175], v165 offset:16
	v_add_f32_e32 v164, 1.0, v164
	v_log_f32_e32 v164, v164
	ds_read_b128 v[176:179], v165 offset:32
	ds_read_b128 v[188:191], v165 offset:48
	s_waitcnt lgkmcnt(2)
	v_mov_b32_e32 v165, v172
	v_mov_b32_e32 v172, v169
	v_mul_f32_e32 v181, 0x3f317218, v164
	v_mov_b32_e32 v164, v168
	v_pk_mul_f32 v[168:169], v[146:147], v[172:173]
	v_fmac_f32_e32 v150, 0xbd800000, v181
	v_pk_fma_f32 v[164:165], v[148:149], v[164:165], v[168:169]
	v_mov_b32_e32 v168, v170
	v_mov_b32_e32 v169, v174
	v_pk_fma_f32 v[164:165], v[144:145], v[168:169], v[164:165]
	v_mov_b32_e32 v174, v171
	v_pk_fma_f32 v[164:165], v[142:143], v[174:175], v[164:165]
	s_nop 0
	v_add_f32_e32 v164, v162, v164
	v_add_f32_e32 v170, v164, v165
	s_waitcnt lgkmcnt(0)
	v_mov_b32_e32 v165, v188
	v_mov_b32_e32 v188, v177
	v_mov_b32_e32 v164, v176
	v_pk_mul_f32 v[168:169], v[140:141], v[188:189]
	s_nop 0
	v_pk_fma_f32 v[164:165], v[138:139], v[164:165], v[168:169]
	v_mov_b32_e32 v168, v178
	v_mov_b32_e32 v169, v190
	v_pk_fma_f32 v[164:165], v[136:137], v[168:169], v[164:165]
	v_mov_b32_e32 v190, v179
	v_pk_fma_f32 v[164:165], v[134:135], v[190:191], v[164:165]
	s_nop 0
	v_add_f32_e32 v164, v170, v164
	v_add_f32_e32 v164, v164, v165
	v_max_f32_e32 v164, 0xc2a00000, v164
	v_mul_f32_e32 v164, 0xbfb8aa3b, v164
	v_exp_f32_e32 v164, v164
	v_lshl_add_u32 v165, v180, 10, v78
	v_or_b32_e32 v180, 6, v163
	ds_write_b32 v165, v150
	v_lshl_add_u32 v165, v180, 6, s2
	ds_read_b128 v[168:171], v165
	ds_read_b128 v[172:175], v165 offset:16
	v_add_f32_e32 v164, 1.0, v164
	v_log_f32_e32 v164, v164
	ds_read_b128 v[176:179], v165 offset:32
	ds_read_b128 v[188:191], v165 offset:48
	s_waitcnt lgkmcnt(2)
	v_mov_b32_e32 v165, v172
	v_mov_b32_e32 v172, v169
	v_mul_f32_e32 v181, 0x3f317218, v164
	v_mov_b32_e32 v164, v168
	v_pk_mul_f32 v[168:169], v[146:147], v[172:173]
	v_fmac_f32_e32 v150, 0xbd800000, v181
	v_pk_fma_f32 v[164:165], v[148:149], v[164:165], v[168:169]
	v_mov_b32_e32 v168, v170
	v_mov_b32_e32 v169, v174
	v_pk_fma_f32 v[164:165], v[144:145], v[168:169], v[164:165]
	v_mov_b32_e32 v174, v171
	v_pk_fma_f32 v[164:165], v[142:143], v[174:175], v[164:165]
	s_nop 0
	v_add_f32_e32 v164, v162, v164
	v_add_f32_e32 v170, v164, v165
	s_waitcnt lgkmcnt(0)
	v_mov_b32_e32 v165, v188
	v_mov_b32_e32 v188, v177
	v_mov_b32_e32 v164, v176
	v_pk_mul_f32 v[168:169], v[140:141], v[188:189]
	s_nop 0
	v_pk_fma_f32 v[164:165], v[138:139], v[164:165], v[168:169]
	v_mov_b32_e32 v168, v178
	v_mov_b32_e32 v169, v190
	v_pk_fma_f32 v[164:165], v[136:137], v[168:169], v[164:165]
	v_mov_b32_e32 v190, v179
	v_pk_fma_f32 v[164:165], v[134:135], v[190:191], v[164:165]
	s_nop 0
	v_add_f32_e32 v164, v170, v164
	v_add_f32_e32 v164, v164, v165
	v_max_f32_e32 v164, 0xc2a00000, v164
	v_mul_f32_e32 v164, 0xbfb8aa3b, v164
	v_exp_f32_e32 v164, v164
	v_lshl_add_u32 v165, v167, 10, v78
	v_or_b32_e32 v167, 7, v163
	ds_write_b32 v165, v150
	v_lshl_add_u32 v165, v167, 6, s2
	ds_read_b128 v[168:171], v165
	ds_read_b128 v[172:175], v165 offset:16
	v_add_f32_e32 v164, 1.0, v164
	v_log_f32_e32 v164, v164
	ds_read_b128 v[176:179], v165 offset:32
	ds_read_b128 v[188:191], v165 offset:48
	s_waitcnt lgkmcnt(2)
	v_mov_b32_e32 v165, v172
	v_mov_b32_e32 v172, v169
	v_mul_f32_e32 v181, 0x3f317218, v164
	v_mov_b32_e32 v164, v168
	v_pk_mul_f32 v[168:169], v[146:147], v[172:173]
	v_fmac_f32_e32 v150, 0xbd800000, v181
	v_pk_fma_f32 v[164:165], v[148:149], v[164:165], v[168:169]
	v_mov_b32_e32 v168, v170
	v_mov_b32_e32 v169, v174
	v_pk_fma_f32 v[164:165], v[144:145], v[168:169], v[164:165]
	v_mov_b32_e32 v174, v171
	v_pk_fma_f32 v[164:165], v[142:143], v[174:175], v[164:165]
	s_nop 0
	v_add_f32_e32 v164, v162, v164
	v_add_f32_e32 v170, v164, v165
	s_waitcnt lgkmcnt(0)
	v_mov_b32_e32 v165, v188
	v_mov_b32_e32 v188, v177
	v_mov_b32_e32 v164, v176
	v_pk_mul_f32 v[168:169], v[140:141], v[188:189]
	s_nop 0
	v_pk_fma_f32 v[164:165], v[138:139], v[164:165], v[168:169]
	v_mov_b32_e32 v168, v178
	v_mov_b32_e32 v169, v190
	v_pk_fma_f32 v[164:165], v[136:137], v[168:169], v[164:165]
	v_mov_b32_e32 v190, v179
	v_pk_fma_f32 v[164:165], v[134:135], v[190:191], v[164:165]
	s_nop 0
	v_add_f32_e32 v164, v170, v164
	v_add_f32_e32 v164, v164, v165
	v_max_f32_e32 v164, 0xc2a00000, v164
	v_mul_f32_e32 v164, 0xbfb8aa3b, v164
	v_exp_f32_e32 v164, v164
	v_lshl_add_u32 v165, v180, 10, v78
	v_or_b32_e32 v180, 8, v163
	ds_write_b32 v165, v150
	v_lshl_add_u32 v165, v180, 6, s2
	ds_read_b128 v[168:171], v165
	ds_read_b128 v[172:175], v165 offset:16
	v_add_f32_e32 v164, 1.0, v164
	v_log_f32_e32 v164, v164
	ds_read_b128 v[176:179], v165 offset:32
	ds_read_b128 v[188:191], v165 offset:48
	s_waitcnt lgkmcnt(2)
	v_mov_b32_e32 v165, v172
	v_mov_b32_e32 v172, v169
	v_mul_f32_e32 v181, 0x3f317218, v164
	v_mov_b32_e32 v164, v168
	v_pk_mul_f32 v[168:169], v[146:147], v[172:173]
	v_fmac_f32_e32 v150, 0xbd800000, v181
	v_pk_fma_f32 v[164:165], v[148:149], v[164:165], v[168:169]
	v_mov_b32_e32 v168, v170
	v_mov_b32_e32 v169, v174
	v_pk_fma_f32 v[164:165], v[144:145], v[168:169], v[164:165]
	v_mov_b32_e32 v174, v171
	v_pk_fma_f32 v[164:165], v[142:143], v[174:175], v[164:165]
	s_nop 0
	v_add_f32_e32 v164, v162, v164
	v_add_f32_e32 v170, v164, v165
	s_waitcnt lgkmcnt(0)
	v_mov_b32_e32 v165, v188
	v_mov_b32_e32 v188, v177
	v_mov_b32_e32 v164, v176
	v_pk_mul_f32 v[168:169], v[140:141], v[188:189]
	s_nop 0
	v_pk_fma_f32 v[164:165], v[138:139], v[164:165], v[168:169]
	v_mov_b32_e32 v168, v178
	v_mov_b32_e32 v169, v190
	v_pk_fma_f32 v[164:165], v[136:137], v[168:169], v[164:165]
	v_mov_b32_e32 v190, v179
	v_pk_fma_f32 v[164:165], v[134:135], v[190:191], v[164:165]
	s_nop 0
	v_add_f32_e32 v164, v170, v164
	v_add_f32_e32 v164, v164, v165
	v_max_f32_e32 v164, 0xc2a00000, v164
	v_mul_f32_e32 v164, 0xbfb8aa3b, v164
	v_exp_f32_e32 v164, v164
	v_lshl_add_u32 v165, v167, 10, v78
	v_or_b32_e32 v167, 9, v163
	ds_write_b32 v165, v150
	v_lshl_add_u32 v165, v167, 6, s2
	ds_read_b128 v[168:171], v165
	ds_read_b128 v[172:175], v165 offset:16
	v_add_f32_e32 v164, 1.0, v164
	v_log_f32_e32 v164, v164
	ds_read_b128 v[176:179], v165 offset:32
	ds_read_b128 v[188:191], v165 offset:48
	s_waitcnt lgkmcnt(2)
	v_mov_b32_e32 v165, v172
	v_mov_b32_e32 v172, v169
	v_mul_f32_e32 v181, 0x3f317218, v164
	v_mov_b32_e32 v164, v168
	v_pk_mul_f32 v[168:169], v[146:147], v[172:173]
	v_fmac_f32_e32 v150, 0xbd800000, v181
	v_pk_fma_f32 v[164:165], v[148:149], v[164:165], v[168:169]
	v_mov_b32_e32 v168, v170
	v_mov_b32_e32 v169, v174
	v_pk_fma_f32 v[164:165], v[144:145], v[168:169], v[164:165]
	v_mov_b32_e32 v174, v171
	v_pk_fma_f32 v[164:165], v[142:143], v[174:175], v[164:165]
	s_nop 0
	v_add_f32_e32 v164, v162, v164
	v_add_f32_e32 v170, v164, v165
	s_waitcnt lgkmcnt(0)
	v_mov_b32_e32 v165, v188
	v_mov_b32_e32 v188, v177
	v_mov_b32_e32 v164, v176
	v_pk_mul_f32 v[168:169], v[140:141], v[188:189]
	s_nop 0
	v_pk_fma_f32 v[164:165], v[138:139], v[164:165], v[168:169]
	v_mov_b32_e32 v168, v178
	v_mov_b32_e32 v169, v190
	v_pk_fma_f32 v[164:165], v[136:137], v[168:169], v[164:165]
	v_mov_b32_e32 v190, v179
	v_pk_fma_f32 v[164:165], v[134:135], v[190:191], v[164:165]
	s_nop 0
	v_add_f32_e32 v164, v170, v164
	v_add_f32_e32 v164, v164, v165
	v_max_f32_e32 v164, 0xc2a00000, v164
	v_mul_f32_e32 v164, 0xbfb8aa3b, v164
	v_exp_f32_e32 v164, v164
	v_lshl_add_u32 v165, v180, 10, v78
	v_or_b32_e32 v180, 10, v163
	ds_write_b32 v165, v150
	v_lshl_add_u32 v165, v180, 6, s2
	ds_read_b128 v[168:171], v165
	ds_read_b128 v[172:175], v165 offset:16
	v_add_f32_e32 v164, 1.0, v164
	v_log_f32_e32 v164, v164
	ds_read_b128 v[176:179], v165 offset:32
	ds_read_b128 v[188:191], v165 offset:48
	s_waitcnt lgkmcnt(2)
	v_mov_b32_e32 v165, v172
	v_mov_b32_e32 v172, v169
	v_mul_f32_e32 v181, 0x3f317218, v164
	v_mov_b32_e32 v164, v168
	v_pk_mul_f32 v[168:169], v[146:147], v[172:173]
	v_fmac_f32_e32 v150, 0xbd800000, v181
	v_pk_fma_f32 v[164:165], v[148:149], v[164:165], v[168:169]
	v_mov_b32_e32 v168, v170
	v_mov_b32_e32 v169, v174
	v_pk_fma_f32 v[164:165], v[144:145], v[168:169], v[164:165]
	v_mov_b32_e32 v174, v171
	v_pk_fma_f32 v[164:165], v[142:143], v[174:175], v[164:165]
	s_nop 0
	v_add_f32_e32 v164, v162, v164
	v_add_f32_e32 v170, v164, v165
	s_waitcnt lgkmcnt(0)
	v_mov_b32_e32 v165, v188
	v_mov_b32_e32 v188, v177
	v_mov_b32_e32 v164, v176
	v_pk_mul_f32 v[168:169], v[140:141], v[188:189]
	s_nop 0
	v_pk_fma_f32 v[164:165], v[138:139], v[164:165], v[168:169]
	v_mov_b32_e32 v168, v178
	v_mov_b32_e32 v169, v190
	v_pk_fma_f32 v[164:165], v[136:137], v[168:169], v[164:165]
	v_mov_b32_e32 v190, v179
	v_pk_fma_f32 v[164:165], v[134:135], v[190:191], v[164:165]
	s_nop 0
	v_add_f32_e32 v164, v170, v164
	v_add_f32_e32 v164, v164, v165
	v_max_f32_e32 v164, 0xc2a00000, v164
	v_mul_f32_e32 v164, 0xbfb8aa3b, v164
	v_exp_f32_e32 v164, v164
	v_lshl_add_u32 v165, v167, 10, v78
	v_or_b32_e32 v167, 11, v163
	ds_write_b32 v165, v150
	v_lshl_add_u32 v165, v167, 6, s2
	ds_read_b128 v[168:171], v165
	ds_read_b128 v[172:175], v165 offset:16
	v_add_f32_e32 v164, 1.0, v164
	v_log_f32_e32 v164, v164
	ds_read_b128 v[176:179], v165 offset:32
	ds_read_b128 v[188:191], v165 offset:48
	s_waitcnt lgkmcnt(2)
	v_mov_b32_e32 v165, v172
	v_mov_b32_e32 v172, v169
	v_mul_f32_e32 v181, 0x3f317218, v164
	v_mov_b32_e32 v164, v168
	v_pk_mul_f32 v[168:169], v[146:147], v[172:173]
	v_fmac_f32_e32 v150, 0xbd800000, v181
	v_pk_fma_f32 v[164:165], v[148:149], v[164:165], v[168:169]
	v_mov_b32_e32 v168, v170
	v_mov_b32_e32 v169, v174
	v_pk_fma_f32 v[164:165], v[144:145], v[168:169], v[164:165]
	v_mov_b32_e32 v174, v171
	v_pk_fma_f32 v[164:165], v[142:143], v[174:175], v[164:165]
	s_nop 0
	v_add_f32_e32 v164, v162, v164
	v_add_f32_e32 v170, v164, v165
	s_waitcnt lgkmcnt(0)
	v_mov_b32_e32 v165, v188
	v_mov_b32_e32 v188, v177
	v_mov_b32_e32 v164, v176
	v_pk_mul_f32 v[168:169], v[140:141], v[188:189]
	s_nop 0
	v_pk_fma_f32 v[164:165], v[138:139], v[164:165], v[168:169]
	v_mov_b32_e32 v168, v178
	v_mov_b32_e32 v169, v190
	v_pk_fma_f32 v[164:165], v[136:137], v[168:169], v[164:165]
	v_mov_b32_e32 v190, v179
	v_pk_fma_f32 v[164:165], v[134:135], v[190:191], v[164:165]
	s_nop 0
	v_add_f32_e32 v164, v170, v164
	v_add_f32_e32 v164, v164, v165
	v_max_f32_e32 v164, 0xc2a00000, v164
	v_mul_f32_e32 v164, 0xbfb8aa3b, v164
	v_exp_f32_e32 v164, v164
	v_lshl_add_u32 v165, v180, 10, v78
	v_or_b32_e32 v180, 12, v163
	ds_write_b32 v165, v150
	v_lshl_add_u32 v165, v180, 6, s2
	ds_read_b128 v[168:171], v165
	ds_read_b128 v[172:175], v165 offset:16
	v_add_f32_e32 v164, 1.0, v164
	v_log_f32_e32 v164, v164
	ds_read_b128 v[176:179], v165 offset:32
	ds_read_b128 v[188:191], v165 offset:48
	s_waitcnt lgkmcnt(2)
	v_mov_b32_e32 v165, v172
	v_mov_b32_e32 v172, v169
	v_mul_f32_e32 v181, 0x3f317218, v164
	v_mov_b32_e32 v164, v168
	v_pk_mul_f32 v[168:169], v[146:147], v[172:173]
	v_fmac_f32_e32 v150, 0xbd800000, v181
	v_pk_fma_f32 v[164:165], v[148:149], v[164:165], v[168:169]
	v_mov_b32_e32 v168, v170
	v_mov_b32_e32 v169, v174
	v_pk_fma_f32 v[164:165], v[144:145], v[168:169], v[164:165]
	v_mov_b32_e32 v174, v171
	v_pk_fma_f32 v[164:165], v[142:143], v[174:175], v[164:165]
	s_nop 0
	v_add_f32_e32 v164, v162, v164
	v_add_f32_e32 v170, v164, v165
	s_waitcnt lgkmcnt(0)
	v_mov_b32_e32 v165, v188
	v_mov_b32_e32 v188, v177
	v_mov_b32_e32 v164, v176
	v_pk_mul_f32 v[168:169], v[140:141], v[188:189]
	s_nop 0
	v_pk_fma_f32 v[164:165], v[138:139], v[164:165], v[168:169]
	v_mov_b32_e32 v168, v178
	v_mov_b32_e32 v169, v190
	v_pk_fma_f32 v[164:165], v[136:137], v[168:169], v[164:165]
	v_mov_b32_e32 v190, v179
	v_pk_fma_f32 v[164:165], v[134:135], v[190:191], v[164:165]
	s_nop 0
	v_add_f32_e32 v164, v170, v164
	v_add_f32_e32 v164, v164, v165
	v_max_f32_e32 v164, 0xc2a00000, v164
	v_mul_f32_e32 v164, 0xbfb8aa3b, v164
	v_exp_f32_e32 v164, v164
	v_lshl_add_u32 v165, v167, 10, v78
	v_or_b32_e32 v167, 13, v163
	ds_write_b32 v165, v150
	v_lshl_add_u32 v165, v167, 6, s2
	ds_read_b128 v[168:171], v165
	ds_read_b128 v[172:175], v165 offset:16
	v_add_f32_e32 v164, 1.0, v164
	v_log_f32_e32 v164, v164
	ds_read_b128 v[176:179], v165 offset:32
	ds_read_b128 v[188:191], v165 offset:48
	s_waitcnt lgkmcnt(2)
	v_mov_b32_e32 v165, v172
	v_mov_b32_e32 v172, v169
	v_mul_f32_e32 v181, 0x3f317218, v164
	v_mov_b32_e32 v164, v168
	v_pk_mul_f32 v[168:169], v[146:147], v[172:173]
	v_fmac_f32_e32 v150, 0xbd800000, v181
	v_pk_fma_f32 v[164:165], v[148:149], v[164:165], v[168:169]
	v_mov_b32_e32 v168, v170
	v_mov_b32_e32 v169, v174
	v_pk_fma_f32 v[164:165], v[144:145], v[168:169], v[164:165]
	v_mov_b32_e32 v174, v171
	v_pk_fma_f32 v[164:165], v[142:143], v[174:175], v[164:165]
	s_nop 0
	v_add_f32_e32 v164, v162, v164
	v_add_f32_e32 v170, v164, v165
	s_waitcnt lgkmcnt(0)
	v_mov_b32_e32 v165, v188
	v_mov_b32_e32 v188, v177
	v_mov_b32_e32 v164, v176
	v_pk_mul_f32 v[168:169], v[140:141], v[188:189]
	s_nop 0
	v_pk_fma_f32 v[164:165], v[138:139], v[164:165], v[168:169]
	v_mov_b32_e32 v168, v178
	v_mov_b32_e32 v169, v190
	v_pk_fma_f32 v[164:165], v[136:137], v[168:169], v[164:165]
	v_mov_b32_e32 v190, v179
	v_pk_fma_f32 v[164:165], v[134:135], v[190:191], v[164:165]
	s_nop 0
	v_add_f32_e32 v164, v170, v164
	v_add_f32_e32 v164, v164, v165
	v_max_f32_e32 v164, 0xc2a00000, v164
	v_mul_f32_e32 v164, 0xbfb8aa3b, v164
	v_exp_f32_e32 v164, v164
	v_lshl_add_u32 v165, v180, 10, v78
	v_or_b32_e32 v180, 14, v163
	ds_write_b32 v165, v150
	v_lshl_add_u32 v165, v180, 6, s2
	ds_read_b128 v[168:171], v165
	ds_read_b128 v[172:175], v165 offset:16
	v_add_f32_e32 v164, 1.0, v164
	v_log_f32_e32 v164, v164
	ds_read_b128 v[176:179], v165 offset:32
	ds_read_b128 v[188:191], v165 offset:48
	s_waitcnt lgkmcnt(2)
	v_mov_b32_e32 v165, v172
	v_mov_b32_e32 v172, v169
	v_mul_f32_e32 v181, 0x3f317218, v164
	v_mov_b32_e32 v164, v168
	v_pk_mul_f32 v[168:169], v[146:147], v[172:173]
	v_fmac_f32_e32 v150, 0xbd800000, v181
	v_pk_fma_f32 v[164:165], v[148:149], v[164:165], v[168:169]
	v_mov_b32_e32 v168, v170
	v_mov_b32_e32 v169, v174
	v_pk_fma_f32 v[164:165], v[144:145], v[168:169], v[164:165]
	v_mov_b32_e32 v174, v171
	v_pk_fma_f32 v[164:165], v[142:143], v[174:175], v[164:165]
	s_nop 0
	v_add_f32_e32 v164, v162, v164
	v_add_f32_e32 v170, v164, v165
	s_waitcnt lgkmcnt(0)
	v_mov_b32_e32 v165, v188
	v_mov_b32_e32 v188, v177
	v_mov_b32_e32 v164, v176
	v_pk_mul_f32 v[168:169], v[140:141], v[188:189]
	s_nop 0
	v_pk_fma_f32 v[164:165], v[138:139], v[164:165], v[168:169]
	v_mov_b32_e32 v168, v178
	v_mov_b32_e32 v169, v190
	v_pk_fma_f32 v[164:165], v[136:137], v[168:169], v[164:165]
	v_mov_b32_e32 v190, v179
	v_pk_fma_f32 v[164:165], v[134:135], v[190:191], v[164:165]
	s_nop 0
	v_add_f32_e32 v164, v170, v164
	v_add_f32_e32 v164, v164, v165
	v_max_f32_e32 v164, 0xc2a00000, v164
	v_mul_f32_e32 v164, 0xbfb8aa3b, v164
	v_exp_f32_e32 v164, v164
	v_lshl_add_u32 v165, v167, 10, v78
	v_or_b32_e32 v167, 15, v163
	ds_write_b32 v165, v150
	v_lshl_add_u32 v165, v167, 6, s2
	ds_read_b128 v[168:171], v165
	ds_read_b128 v[172:175], v165 offset:16
	v_add_f32_e32 v164, 1.0, v164
	v_log_f32_e32 v164, v164
	ds_read_b128 v[176:179], v165 offset:32
	ds_read_b128 v[188:191], v165 offset:48
	s_waitcnt lgkmcnt(2)
	v_mov_b32_e32 v165, v172
	v_mov_b32_e32 v172, v169
	v_mul_f32_e32 v181, 0x3f317218, v164
	v_mov_b32_e32 v164, v168
	v_pk_mul_f32 v[168:169], v[146:147], v[172:173]
	v_fmac_f32_e32 v150, 0xbd800000, v181
	v_pk_fma_f32 v[164:165], v[148:149], v[164:165], v[168:169]
	v_mov_b32_e32 v168, v170
	v_mov_b32_e32 v169, v174
	v_pk_fma_f32 v[164:165], v[144:145], v[168:169], v[164:165]
	v_mov_b32_e32 v174, v171
	v_pk_fma_f32 v[164:165], v[142:143], v[174:175], v[164:165]
	s_nop 0
	v_add_f32_e32 v164, v162, v164
	v_add_f32_e32 v170, v164, v165
	s_waitcnt lgkmcnt(0)
	v_mov_b32_e32 v165, v188
	v_mov_b32_e32 v188, v177
	v_mov_b32_e32 v164, v176
	v_pk_mul_f32 v[168:169], v[140:141], v[188:189]
	s_nop 0
	v_pk_fma_f32 v[164:165], v[138:139], v[164:165], v[168:169]
	v_mov_b32_e32 v168, v178
	v_mov_b32_e32 v169, v190
	v_pk_fma_f32 v[164:165], v[136:137], v[168:169], v[164:165]
	v_mov_b32_e32 v190, v179
	v_pk_fma_f32 v[164:165], v[134:135], v[190:191], v[164:165]
	s_nop 0
	v_add_f32_e32 v164, v170, v164
	v_add_f32_e32 v164, v164, v165
	v_max_f32_e32 v164, 0xc2a00000, v164
	v_mul_f32_e32 v164, 0xbfb8aa3b, v164
	v_exp_f32_e32 v164, v164
	v_lshl_add_u32 v165, v180, 10, v78
	v_or_b32_e32 v180, 16, v163
	ds_write_b32 v165, v150
	v_lshl_add_u32 v165, v180, 6, s2
	ds_read_b128 v[168:171], v165
	ds_read_b128 v[172:175], v165 offset:16
	v_add_f32_e32 v164, 1.0, v164
	v_log_f32_e32 v164, v164
	ds_read_b128 v[176:179], v165 offset:32
	ds_read_b128 v[188:191], v165 offset:48
	s_waitcnt lgkmcnt(2)
	v_mov_b32_e32 v165, v172
	v_mov_b32_e32 v172, v169
	v_mul_f32_e32 v181, 0x3f317218, v164
	v_mov_b32_e32 v164, v168
	v_pk_mul_f32 v[168:169], v[146:147], v[172:173]
	v_fmac_f32_e32 v150, 0xbd800000, v181
	v_pk_fma_f32 v[164:165], v[148:149], v[164:165], v[168:169]
	v_mov_b32_e32 v168, v170
	v_mov_b32_e32 v169, v174
	v_pk_fma_f32 v[164:165], v[144:145], v[168:169], v[164:165]
	v_mov_b32_e32 v174, v171
	v_pk_fma_f32 v[164:165], v[142:143], v[174:175], v[164:165]
	s_nop 0
	v_add_f32_e32 v164, v162, v164
	v_add_f32_e32 v170, v164, v165
	s_waitcnt lgkmcnt(0)
	v_mov_b32_e32 v165, v188
	v_mov_b32_e32 v188, v177
	v_mov_b32_e32 v164, v176
	v_pk_mul_f32 v[168:169], v[140:141], v[188:189]
	s_nop 0
	v_pk_fma_f32 v[164:165], v[138:139], v[164:165], v[168:169]
	v_mov_b32_e32 v168, v178
	v_mov_b32_e32 v169, v190
	v_pk_fma_f32 v[164:165], v[136:137], v[168:169], v[164:165]
	v_mov_b32_e32 v190, v179
	v_pk_fma_f32 v[164:165], v[134:135], v[190:191], v[164:165]
	s_nop 0
	v_add_f32_e32 v164, v170, v164
	v_add_f32_e32 v164, v164, v165
	v_max_f32_e32 v164, 0xc2a00000, v164
	v_mul_f32_e32 v164, 0xbfb8aa3b, v164
	v_exp_f32_e32 v164, v164
	v_lshl_add_u32 v165, v167, 10, v78
	v_or_b32_e32 v167, 17, v163
	ds_write_b32 v165, v150
	v_lshl_add_u32 v165, v167, 6, s2
	ds_read_b128 v[168:171], v165
	ds_read_b128 v[172:175], v165 offset:16
	v_add_f32_e32 v164, 1.0, v164
	v_log_f32_e32 v164, v164
	ds_read_b128 v[176:179], v165 offset:32
	ds_read_b128 v[188:191], v165 offset:48
	s_waitcnt lgkmcnt(2)
	v_mov_b32_e32 v165, v172
	v_mov_b32_e32 v172, v169
	v_mul_f32_e32 v181, 0x3f317218, v164
	v_mov_b32_e32 v164, v168
	v_pk_mul_f32 v[168:169], v[146:147], v[172:173]
	v_fmac_f32_e32 v150, 0xbd800000, v181
	v_pk_fma_f32 v[164:165], v[148:149], v[164:165], v[168:169]
	v_mov_b32_e32 v168, v170
	v_mov_b32_e32 v169, v174
	v_pk_fma_f32 v[164:165], v[144:145], v[168:169], v[164:165]
	v_mov_b32_e32 v174, v171
	v_pk_fma_f32 v[164:165], v[142:143], v[174:175], v[164:165]
	s_nop 0
	v_add_f32_e32 v164, v162, v164
	v_add_f32_e32 v170, v164, v165
	s_waitcnt lgkmcnt(0)
	v_mov_b32_e32 v165, v188
	v_mov_b32_e32 v188, v177
	v_mov_b32_e32 v164, v176
	v_pk_mul_f32 v[168:169], v[140:141], v[188:189]
	s_nop 0
	v_pk_fma_f32 v[164:165], v[138:139], v[164:165], v[168:169]
	v_mov_b32_e32 v168, v178
	v_mov_b32_e32 v169, v190
	v_pk_fma_f32 v[164:165], v[136:137], v[168:169], v[164:165]
	v_mov_b32_e32 v190, v179
	v_pk_fma_f32 v[164:165], v[134:135], v[190:191], v[164:165]
	s_nop 0
	v_add_f32_e32 v164, v170, v164
	v_add_f32_e32 v164, v164, v165
	v_max_f32_e32 v164, 0xc2a00000, v164
	v_mul_f32_e32 v164, 0xbfb8aa3b, v164
	v_exp_f32_e32 v164, v164
	v_lshl_add_u32 v165, v180, 10, v78
	v_or_b32_e32 v180, 18, v163
	ds_write_b32 v165, v150
	v_lshl_add_u32 v165, v180, 6, s2
	ds_read_b128 v[168:171], v165
	ds_read_b128 v[172:175], v165 offset:16
	v_add_f32_e32 v164, 1.0, v164
	v_log_f32_e32 v164, v164
	ds_read_b128 v[176:179], v165 offset:32
	ds_read_b128 v[188:191], v165 offset:48
	s_waitcnt lgkmcnt(2)
	v_mov_b32_e32 v165, v172
	v_mov_b32_e32 v172, v169
	v_mul_f32_e32 v181, 0x3f317218, v164
	v_mov_b32_e32 v164, v168
	v_pk_mul_f32 v[168:169], v[146:147], v[172:173]
	v_fmac_f32_e32 v150, 0xbd800000, v181
	v_pk_fma_f32 v[164:165], v[148:149], v[164:165], v[168:169]
	v_mov_b32_e32 v168, v170
	v_mov_b32_e32 v169, v174
	v_pk_fma_f32 v[164:165], v[144:145], v[168:169], v[164:165]
	v_mov_b32_e32 v174, v171
	v_pk_fma_f32 v[164:165], v[142:143], v[174:175], v[164:165]
	s_nop 0
	v_add_f32_e32 v164, v162, v164
	v_add_f32_e32 v170, v164, v165
	s_waitcnt lgkmcnt(0)
	v_mov_b32_e32 v165, v188
	v_mov_b32_e32 v188, v177
	v_mov_b32_e32 v164, v176
	v_pk_mul_f32 v[168:169], v[140:141], v[188:189]
	s_nop 0
	v_pk_fma_f32 v[164:165], v[138:139], v[164:165], v[168:169]
	v_mov_b32_e32 v168, v178
	v_mov_b32_e32 v169, v190
	v_pk_fma_f32 v[164:165], v[136:137], v[168:169], v[164:165]
	v_mov_b32_e32 v190, v179
	v_pk_fma_f32 v[164:165], v[134:135], v[190:191], v[164:165]
	s_nop 0
	v_add_f32_e32 v164, v170, v164
	v_add_f32_e32 v164, v164, v165
	v_max_f32_e32 v164, 0xc2a00000, v164
	v_mul_f32_e32 v164, 0xbfb8aa3b, v164
	v_exp_f32_e32 v164, v164
	v_lshl_add_u32 v165, v167, 10, v78
	v_or_b32_e32 v167, 19, v163
	ds_write_b32 v165, v150
	v_lshl_add_u32 v165, v167, 6, s2
	ds_read_b128 v[168:171], v165
	ds_read_b128 v[172:175], v165 offset:16
	v_add_f32_e32 v164, 1.0, v164
	v_log_f32_e32 v164, v164
	ds_read_b128 v[176:179], v165 offset:32
	ds_read_b128 v[188:191], v165 offset:48
	s_waitcnt lgkmcnt(2)
	v_mov_b32_e32 v165, v172
	v_mov_b32_e32 v172, v169
	v_mul_f32_e32 v181, 0x3f317218, v164
	v_mov_b32_e32 v164, v168
	v_pk_mul_f32 v[168:169], v[146:147], v[172:173]
	v_fmac_f32_e32 v150, 0xbd800000, v181
	v_pk_fma_f32 v[164:165], v[148:149], v[164:165], v[168:169]
	v_mov_b32_e32 v168, v170
	v_mov_b32_e32 v169, v174
	v_pk_fma_f32 v[164:165], v[144:145], v[168:169], v[164:165]
	v_mov_b32_e32 v174, v171
	v_pk_fma_f32 v[164:165], v[142:143], v[174:175], v[164:165]
	s_nop 0
	v_add_f32_e32 v164, v162, v164
	v_add_f32_e32 v170, v164, v165
	s_waitcnt lgkmcnt(0)
	v_mov_b32_e32 v165, v188
	v_mov_b32_e32 v188, v177
	v_mov_b32_e32 v164, v176
	v_pk_mul_f32 v[168:169], v[140:141], v[188:189]
	s_nop 0
	v_pk_fma_f32 v[164:165], v[138:139], v[164:165], v[168:169]
	v_mov_b32_e32 v168, v178
	v_mov_b32_e32 v169, v190
	v_pk_fma_f32 v[164:165], v[136:137], v[168:169], v[164:165]
	v_mov_b32_e32 v190, v179
	v_pk_fma_f32 v[164:165], v[134:135], v[190:191], v[164:165]
	s_nop 0
	v_add_f32_e32 v164, v170, v164
	v_add_f32_e32 v164, v164, v165
	v_max_f32_e32 v164, 0xc2a00000, v164
	v_mul_f32_e32 v164, 0xbfb8aa3b, v164
	v_exp_f32_e32 v164, v164
	v_lshl_add_u32 v165, v180, 10, v78
	v_or_b32_e32 v180, 20, v163
	ds_write_b32 v165, v150
	v_lshl_add_u32 v165, v180, 6, s2
	ds_read_b128 v[168:171], v165
	ds_read_b128 v[172:175], v165 offset:16
	v_add_f32_e32 v164, 1.0, v164
	v_log_f32_e32 v164, v164
	ds_read_b128 v[176:179], v165 offset:32
	ds_read_b128 v[188:191], v165 offset:48
	s_waitcnt lgkmcnt(2)
	v_mov_b32_e32 v165, v172
	v_mov_b32_e32 v172, v169
	v_mul_f32_e32 v181, 0x3f317218, v164
	v_mov_b32_e32 v164, v168
	v_pk_mul_f32 v[168:169], v[146:147], v[172:173]
	v_fmac_f32_e32 v150, 0xbd800000, v181
	v_pk_fma_f32 v[164:165], v[148:149], v[164:165], v[168:169]
	v_mov_b32_e32 v168, v170
	v_mov_b32_e32 v169, v174
	v_pk_fma_f32 v[164:165], v[144:145], v[168:169], v[164:165]
	v_mov_b32_e32 v174, v171
	v_pk_fma_f32 v[164:165], v[142:143], v[174:175], v[164:165]
	s_nop 0
	v_add_f32_e32 v164, v162, v164
	v_add_f32_e32 v170, v164, v165
	s_waitcnt lgkmcnt(0)
	v_mov_b32_e32 v165, v188
	v_mov_b32_e32 v188, v177
	v_mov_b32_e32 v164, v176
	v_pk_mul_f32 v[168:169], v[140:141], v[188:189]
	s_nop 0
	v_pk_fma_f32 v[164:165], v[138:139], v[164:165], v[168:169]
	v_mov_b32_e32 v168, v178
	v_mov_b32_e32 v169, v190
	v_pk_fma_f32 v[164:165], v[136:137], v[168:169], v[164:165]
	v_mov_b32_e32 v190, v179
	v_pk_fma_f32 v[164:165], v[134:135], v[190:191], v[164:165]
	s_nop 0
	v_add_f32_e32 v164, v170, v164
	v_add_f32_e32 v164, v164, v165
	v_max_f32_e32 v164, 0xc2a00000, v164
	v_mul_f32_e32 v164, 0xbfb8aa3b, v164
	v_exp_f32_e32 v164, v164
	v_lshl_add_u32 v165, v167, 10, v78
	v_or_b32_e32 v167, 21, v163
	ds_write_b32 v165, v150
	v_lshl_add_u32 v165, v167, 6, s2
	ds_read_b128 v[168:171], v165
	ds_read_b128 v[172:175], v165 offset:16
	v_add_f32_e32 v164, 1.0, v164
	v_log_f32_e32 v164, v164
	ds_read_b128 v[176:179], v165 offset:32
	ds_read_b128 v[188:191], v165 offset:48
	s_waitcnt lgkmcnt(2)
	v_mov_b32_e32 v165, v172
	v_mov_b32_e32 v172, v169
	v_mul_f32_e32 v181, 0x3f317218, v164
	v_mov_b32_e32 v164, v168
	v_pk_mul_f32 v[168:169], v[146:147], v[172:173]
	v_fmac_f32_e32 v150, 0xbd800000, v181
	v_pk_fma_f32 v[164:165], v[148:149], v[164:165], v[168:169]
	v_mov_b32_e32 v168, v170
	v_mov_b32_e32 v169, v174
	v_pk_fma_f32 v[164:165], v[144:145], v[168:169], v[164:165]
	v_mov_b32_e32 v174, v171
	v_pk_fma_f32 v[164:165], v[142:143], v[174:175], v[164:165]
	s_nop 0
	v_add_f32_e32 v164, v162, v164
	v_add_f32_e32 v170, v164, v165
	s_waitcnt lgkmcnt(0)
	v_mov_b32_e32 v165, v188
	v_mov_b32_e32 v188, v177
	v_mov_b32_e32 v164, v176
	v_pk_mul_f32 v[168:169], v[140:141], v[188:189]
	s_nop 0
	v_pk_fma_f32 v[164:165], v[138:139], v[164:165], v[168:169]
	v_mov_b32_e32 v168, v178
	v_mov_b32_e32 v169, v190
	v_pk_fma_f32 v[164:165], v[136:137], v[168:169], v[164:165]
	v_mov_b32_e32 v190, v179
	v_pk_fma_f32 v[164:165], v[134:135], v[190:191], v[164:165]
	s_nop 0
	v_add_f32_e32 v164, v170, v164
	v_add_f32_e32 v164, v164, v165
	v_max_f32_e32 v164, 0xc2a00000, v164
	v_mul_f32_e32 v164, 0xbfb8aa3b, v164
	v_exp_f32_e32 v164, v164
	v_lshl_add_u32 v165, v180, 10, v78
	v_or_b32_e32 v180, 22, v163
	ds_write_b32 v165, v150
	v_lshl_add_u32 v165, v180, 6, s2
	ds_read_b128 v[168:171], v165
	ds_read_b128 v[172:175], v165 offset:16
	v_add_f32_e32 v164, 1.0, v164
	v_log_f32_e32 v164, v164
	ds_read_b128 v[176:179], v165 offset:32
	ds_read_b128 v[188:191], v165 offset:48
	s_waitcnt lgkmcnt(2)
	v_mov_b32_e32 v165, v172
	v_mov_b32_e32 v172, v169
	v_mul_f32_e32 v181, 0x3f317218, v164
	v_mov_b32_e32 v164, v168
	v_pk_mul_f32 v[168:169], v[146:147], v[172:173]
	v_fmac_f32_e32 v150, 0xbd800000, v181
	v_pk_fma_f32 v[164:165], v[148:149], v[164:165], v[168:169]
	v_mov_b32_e32 v168, v170
	v_mov_b32_e32 v169, v174
	v_pk_fma_f32 v[164:165], v[144:145], v[168:169], v[164:165]
	v_mov_b32_e32 v174, v171
	v_pk_fma_f32 v[164:165], v[142:143], v[174:175], v[164:165]
	s_nop 0
	v_add_f32_e32 v164, v162, v164
	v_add_f32_e32 v170, v164, v165
	s_waitcnt lgkmcnt(0)
	v_mov_b32_e32 v165, v188
	v_mov_b32_e32 v188, v177
	v_mov_b32_e32 v164, v176
	v_pk_mul_f32 v[168:169], v[140:141], v[188:189]
	s_nop 0
	v_pk_fma_f32 v[164:165], v[138:139], v[164:165], v[168:169]
	v_mov_b32_e32 v168, v178
	v_mov_b32_e32 v169, v190
	v_pk_fma_f32 v[164:165], v[136:137], v[168:169], v[164:165]
	v_mov_b32_e32 v190, v179
	v_pk_fma_f32 v[164:165], v[134:135], v[190:191], v[164:165]
	s_nop 0
	v_add_f32_e32 v164, v170, v164
	v_add_f32_e32 v164, v164, v165
	v_max_f32_e32 v164, 0xc2a00000, v164
	v_mul_f32_e32 v164, 0xbfb8aa3b, v164
	v_exp_f32_e32 v164, v164
	v_lshl_add_u32 v165, v167, 10, v78
	v_or_b32_e32 v167, 23, v163
	ds_write_b32 v165, v150
	v_lshl_add_u32 v165, v167, 6, s2
	ds_read_b128 v[168:171], v165
	ds_read_b128 v[172:175], v165 offset:16
	v_add_f32_e32 v164, 1.0, v164
	v_log_f32_e32 v164, v164
	ds_read_b128 v[176:179], v165 offset:32
	ds_read_b128 v[188:191], v165 offset:48
	s_waitcnt lgkmcnt(2)
	v_mov_b32_e32 v165, v172
	v_mov_b32_e32 v172, v169
	v_mul_f32_e32 v181, 0x3f317218, v164
	v_mov_b32_e32 v164, v168
	v_pk_mul_f32 v[168:169], v[146:147], v[172:173]
	v_fmac_f32_e32 v150, 0xbd800000, v181
	v_pk_fma_f32 v[164:165], v[148:149], v[164:165], v[168:169]
	v_mov_b32_e32 v168, v170
	v_mov_b32_e32 v169, v174
	v_pk_fma_f32 v[164:165], v[144:145], v[168:169], v[164:165]
	v_mov_b32_e32 v174, v171
	v_pk_fma_f32 v[164:165], v[142:143], v[174:175], v[164:165]
	s_nop 0
	v_add_f32_e32 v164, v162, v164
	v_add_f32_e32 v170, v164, v165
	s_waitcnt lgkmcnt(0)
	v_mov_b32_e32 v165, v188
	v_mov_b32_e32 v188, v177
	v_mov_b32_e32 v164, v176
	v_pk_mul_f32 v[168:169], v[140:141], v[188:189]
	s_nop 0
	v_pk_fma_f32 v[164:165], v[138:139], v[164:165], v[168:169]
	v_mov_b32_e32 v168, v178
	v_mov_b32_e32 v169, v190
	v_pk_fma_f32 v[164:165], v[136:137], v[168:169], v[164:165]
	v_mov_b32_e32 v190, v179
	v_pk_fma_f32 v[164:165], v[134:135], v[190:191], v[164:165]
	s_nop 0
	v_add_f32_e32 v164, v170, v164
	v_add_f32_e32 v164, v164, v165
	v_max_f32_e32 v164, 0xc2a00000, v164
	v_mul_f32_e32 v164, 0xbfb8aa3b, v164
	v_exp_f32_e32 v164, v164
	v_lshl_add_u32 v165, v180, 10, v78
	v_or_b32_e32 v180, 24, v163
	ds_write_b32 v165, v150
	v_lshl_add_u32 v165, v180, 6, s2
	ds_read_b128 v[168:171], v165
	ds_read_b128 v[172:175], v165 offset:16
	v_add_f32_e32 v164, 1.0, v164
	v_log_f32_e32 v164, v164
	ds_read_b128 v[176:179], v165 offset:32
	ds_read_b128 v[188:191], v165 offset:48
	s_waitcnt lgkmcnt(2)
	v_mov_b32_e32 v165, v172
	v_mov_b32_e32 v172, v169
	v_mul_f32_e32 v181, 0x3f317218, v164
	v_mov_b32_e32 v164, v168
	v_pk_mul_f32 v[168:169], v[146:147], v[172:173]
	v_fmac_f32_e32 v150, 0xbd800000, v181
	v_pk_fma_f32 v[164:165], v[148:149], v[164:165], v[168:169]
	v_mov_b32_e32 v168, v170
	v_mov_b32_e32 v169, v174
	v_pk_fma_f32 v[164:165], v[144:145], v[168:169], v[164:165]
	v_mov_b32_e32 v174, v171
	v_pk_fma_f32 v[164:165], v[142:143], v[174:175], v[164:165]
	s_nop 0
	v_add_f32_e32 v164, v162, v164
	v_add_f32_e32 v170, v164, v165
	s_waitcnt lgkmcnt(0)
	v_mov_b32_e32 v165, v188
	v_mov_b32_e32 v188, v177
	v_mov_b32_e32 v164, v176
	v_pk_mul_f32 v[168:169], v[140:141], v[188:189]
	s_nop 0
	v_pk_fma_f32 v[164:165], v[138:139], v[164:165], v[168:169]
	v_mov_b32_e32 v168, v178
	v_mov_b32_e32 v169, v190
	v_pk_fma_f32 v[164:165], v[136:137], v[168:169], v[164:165]
	v_mov_b32_e32 v190, v179
	v_pk_fma_f32 v[164:165], v[134:135], v[190:191], v[164:165]
	s_nop 0
	v_add_f32_e32 v164, v170, v164
	v_add_f32_e32 v164, v164, v165
	v_max_f32_e32 v164, 0xc2a00000, v164
	v_mul_f32_e32 v164, 0xbfb8aa3b, v164
	v_exp_f32_e32 v164, v164
	v_lshl_add_u32 v165, v167, 10, v78
	v_or_b32_e32 v167, 25, v163
	ds_write_b32 v165, v150
	v_lshl_add_u32 v165, v167, 6, s2
	ds_read_b128 v[168:171], v165
	ds_read_b128 v[172:175], v165 offset:16
	v_add_f32_e32 v164, 1.0, v164
	v_log_f32_e32 v164, v164
	ds_read_b128 v[176:179], v165 offset:32
	ds_read_b128 v[188:191], v165 offset:48
	s_waitcnt lgkmcnt(2)
	v_mov_b32_e32 v165, v172
	v_mov_b32_e32 v172, v169
	v_mul_f32_e32 v181, 0x3f317218, v164
	v_mov_b32_e32 v164, v168
	v_pk_mul_f32 v[168:169], v[146:147], v[172:173]
	v_fmac_f32_e32 v150, 0xbd800000, v181
	v_pk_fma_f32 v[164:165], v[148:149], v[164:165], v[168:169]
	v_mov_b32_e32 v168, v170
	v_mov_b32_e32 v169, v174
	v_pk_fma_f32 v[164:165], v[144:145], v[168:169], v[164:165]
	v_mov_b32_e32 v174, v171
	v_pk_fma_f32 v[164:165], v[142:143], v[174:175], v[164:165]
	s_nop 0
	v_add_f32_e32 v164, v162, v164
	v_add_f32_e32 v170, v164, v165
	s_waitcnt lgkmcnt(0)
	v_mov_b32_e32 v165, v188
	v_mov_b32_e32 v188, v177
	v_mov_b32_e32 v164, v176
	v_pk_mul_f32 v[168:169], v[140:141], v[188:189]
	s_nop 0
	v_pk_fma_f32 v[164:165], v[138:139], v[164:165], v[168:169]
	v_mov_b32_e32 v168, v178
	v_mov_b32_e32 v169, v190
	v_pk_fma_f32 v[164:165], v[136:137], v[168:169], v[164:165]
	v_mov_b32_e32 v190, v179
	v_pk_fma_f32 v[164:165], v[134:135], v[190:191], v[164:165]
	s_nop 0
	v_add_f32_e32 v164, v170, v164
	v_add_f32_e32 v164, v164, v165
	v_max_f32_e32 v164, 0xc2a00000, v164
	v_mul_f32_e32 v164, 0xbfb8aa3b, v164
	v_exp_f32_e32 v164, v164
	v_lshl_add_u32 v165, v180, 10, v78
	v_or_b32_e32 v180, 26, v163
	ds_write_b32 v165, v150
	v_lshl_add_u32 v165, v180, 6, s2
	ds_read_b128 v[168:171], v165
	ds_read_b128 v[172:175], v165 offset:16
	v_add_f32_e32 v164, 1.0, v164
	v_log_f32_e32 v164, v164
	ds_read_b128 v[176:179], v165 offset:32
	ds_read_b128 v[188:191], v165 offset:48
	s_waitcnt lgkmcnt(2)
	v_mov_b32_e32 v165, v172
	v_mov_b32_e32 v172, v169
	v_mul_f32_e32 v181, 0x3f317218, v164
	v_mov_b32_e32 v164, v168
	v_pk_mul_f32 v[168:169], v[146:147], v[172:173]
	v_fmac_f32_e32 v150, 0xbd800000, v181
	v_pk_fma_f32 v[164:165], v[148:149], v[164:165], v[168:169]
	v_mov_b32_e32 v168, v170
	v_mov_b32_e32 v169, v174
	v_pk_fma_f32 v[164:165], v[144:145], v[168:169], v[164:165]
	v_mov_b32_e32 v174, v171
	v_pk_fma_f32 v[164:165], v[142:143], v[174:175], v[164:165]
	s_nop 0
	v_add_f32_e32 v164, v162, v164
	v_add_f32_e32 v170, v164, v165
	s_waitcnt lgkmcnt(0)
	v_mov_b32_e32 v165, v188
	v_mov_b32_e32 v188, v177
	v_mov_b32_e32 v164, v176
	v_pk_mul_f32 v[168:169], v[140:141], v[188:189]
	s_nop 0
	v_pk_fma_f32 v[164:165], v[138:139], v[164:165], v[168:169]
	v_mov_b32_e32 v168, v178
	v_mov_b32_e32 v169, v190
	v_pk_fma_f32 v[164:165], v[136:137], v[168:169], v[164:165]
	v_mov_b32_e32 v190, v179
	v_pk_fma_f32 v[164:165], v[134:135], v[190:191], v[164:165]
	s_nop 0
	v_add_f32_e32 v164, v170, v164
	v_add_f32_e32 v164, v164, v165
	v_max_f32_e32 v164, 0xc2a00000, v164
	v_mul_f32_e32 v164, 0xbfb8aa3b, v164
	v_exp_f32_e32 v164, v164
	v_lshl_add_u32 v165, v167, 10, v78
	v_or_b32_e32 v167, 27, v163
	ds_write_b32 v165, v150
	v_lshl_add_u32 v165, v167, 6, s2
	ds_read_b128 v[168:171], v165
	ds_read_b128 v[172:175], v165 offset:16
	v_add_f32_e32 v164, 1.0, v164
	v_log_f32_e32 v164, v164
	ds_read_b128 v[176:179], v165 offset:32
	ds_read_b128 v[188:191], v165 offset:48
	s_waitcnt lgkmcnt(2)
	v_mov_b32_e32 v165, v172
	v_mov_b32_e32 v172, v169
	v_mul_f32_e32 v181, 0x3f317218, v164
	v_mov_b32_e32 v164, v168
	v_pk_mul_f32 v[168:169], v[146:147], v[172:173]
	v_fmac_f32_e32 v150, 0xbd800000, v181
	v_pk_fma_f32 v[164:165], v[148:149], v[164:165], v[168:169]
	v_mov_b32_e32 v168, v170
	v_mov_b32_e32 v169, v174
	v_pk_fma_f32 v[164:165], v[144:145], v[168:169], v[164:165]
	v_mov_b32_e32 v174, v171
	v_pk_fma_f32 v[164:165], v[142:143], v[174:175], v[164:165]
	s_nop 0
	v_add_f32_e32 v164, v162, v164
	v_add_f32_e32 v170, v164, v165
	s_waitcnt lgkmcnt(0)
	v_mov_b32_e32 v165, v188
	v_mov_b32_e32 v188, v177
	v_mov_b32_e32 v164, v176
	v_pk_mul_f32 v[168:169], v[140:141], v[188:189]
	s_nop 0
	v_pk_fma_f32 v[164:165], v[138:139], v[164:165], v[168:169]
	v_mov_b32_e32 v168, v178
	v_mov_b32_e32 v169, v190
	v_pk_fma_f32 v[164:165], v[136:137], v[168:169], v[164:165]
	v_mov_b32_e32 v190, v179
	v_pk_fma_f32 v[164:165], v[134:135], v[190:191], v[164:165]
	s_nop 0
	v_add_f32_e32 v164, v170, v164
	v_add_f32_e32 v164, v164, v165
	v_max_f32_e32 v164, 0xc2a00000, v164
	v_mul_f32_e32 v164, 0xbfb8aa3b, v164
	v_exp_f32_e32 v164, v164
	v_lshl_add_u32 v165, v180, 10, v78
	v_or_b32_e32 v180, 28, v163
	ds_write_b32 v165, v150
	v_lshl_add_u32 v165, v180, 6, s2
	ds_read_b128 v[168:171], v165
	ds_read_b128 v[172:175], v165 offset:16
	v_add_f32_e32 v164, 1.0, v164
	v_log_f32_e32 v164, v164
	ds_read_b128 v[176:179], v165 offset:32
	ds_read_b128 v[188:191], v165 offset:48
	v_lshl_add_u32 v180, v180, 10, v78
	s_waitcnt lgkmcnt(2)
	v_mov_b32_e32 v165, v172
	v_mov_b32_e32 v172, v169
	v_mul_f32_e32 v181, 0x3f317218, v164
	v_mov_b32_e32 v164, v168
	v_pk_mul_f32 v[168:169], v[146:147], v[172:173]
	v_fmac_f32_e32 v150, 0xbd800000, v181
	v_pk_fma_f32 v[164:165], v[148:149], v[164:165], v[168:169]
	v_mov_b32_e32 v168, v170
	v_mov_b32_e32 v169, v174
	v_pk_fma_f32 v[164:165], v[144:145], v[168:169], v[164:165]
	v_mov_b32_e32 v174, v171
	v_pk_fma_f32 v[164:165], v[142:143], v[174:175], v[164:165]
	s_nop 0
	v_add_f32_e32 v164, v162, v164
	v_add_f32_e32 v170, v164, v165
	s_waitcnt lgkmcnt(0)
	v_mov_b32_e32 v165, v188
	v_mov_b32_e32 v188, v177
	v_mov_b32_e32 v164, v176
	v_pk_mul_f32 v[168:169], v[140:141], v[188:189]
	s_nop 0
	v_pk_fma_f32 v[164:165], v[138:139], v[164:165], v[168:169]
	v_mov_b32_e32 v168, v178
	v_mov_b32_e32 v169, v190
	v_pk_fma_f32 v[164:165], v[136:137], v[168:169], v[164:165]
	v_mov_b32_e32 v190, v179
	v_pk_fma_f32 v[164:165], v[134:135], v[190:191], v[164:165]
	s_nop 0
	v_add_f32_e32 v164, v170, v164
	v_add_f32_e32 v164, v164, v165
	v_lshl_add_u32 v165, v167, 10, v78
	v_or_b32_e32 v167, 29, v163
	v_max_f32_e32 v164, 0xc2a00000, v164
	ds_write_b32 v165, v150
	v_lshl_add_u32 v165, v167, 6, s2
	v_mul_f32_e32 v164, 0xbfb8aa3b, v164
	ds_read_b128 v[168:171], v165
	ds_read_b128 v[172:175], v165 offset:16
	v_exp_f32_e32 v164, v164
	ds_read_b128 v[176:179], v165 offset:32
	ds_read_b128 v[188:191], v165 offset:48
	v_or_b32_e32 v163, 30, v163
	v_add_f32_e32 v164, 1.0, v164
	s_waitcnt lgkmcnt(2)
	v_mov_b32_e32 v165, v172
	v_mov_b32_e32 v172, v169
	v_log_f32_e32 v181, v164
	v_mov_b32_e32 v164, v168
	v_pk_mul_f32 v[168:169], v[146:147], v[172:173]
	s_nop 0
	v_pk_fma_f32 v[164:165], v[148:149], v[164:165], v[168:169]
	v_mov_b32_e32 v168, v170
	v_mov_b32_e32 v169, v174
	v_pk_fma_f32 v[164:165], v[144:145], v[168:169], v[164:165]
	v_mov_b32_e32 v174, v171
	v_pk_fma_f32 v[164:165], v[142:143], v[174:175], v[164:165]
	s_nop 0
	v_add_f32_e32 v164, v162, v164
	v_add_f32_e32 v170, v164, v165
	s_waitcnt lgkmcnt(0)
	v_mov_b32_e32 v165, v188
	v_mov_b32_e32 v188, v177
	v_mov_b32_e32 v164, v176
	v_pk_mul_f32 v[168:169], v[140:141], v[188:189]
	s_nop 0
	v_pk_fma_f32 v[164:165], v[138:139], v[164:165], v[168:169]
	v_mov_b32_e32 v168, v178
	v_mov_b32_e32 v169, v190
	v_pk_fma_f32 v[164:165], v[136:137], v[168:169], v[164:165]
	v_mov_b32_e32 v190, v179
	v_pk_fma_f32 v[164:165], v[134:135], v[190:191], v[164:165]
	s_nop 0
	v_add_f32_e32 v164, v170, v164
	v_add_f32_e32 v164, v164, v165
	v_mul_f32_e32 v165, 0x3f317218, v181
	v_max_f32_e32 v164, 0xc2a00000, v164
	v_fmac_f32_e32 v150, 0xbd800000, v165
	v_lshl_add_u32 v165, v163, 6, s2
	v_mul_f32_e32 v164, 0xbfb8aa3b, v164
	ds_read_b128 v[168:171], v165
	ds_read_b128 v[172:175], v165 offset:16
	v_exp_f32_e32 v164, v164
	ds_read_b128 v[176:179], v165 offset:32
	ds_read_b128 v[188:191], v165 offset:48
	ds_write_b32 v180, v150
	v_add_f32_e32 v164, 1.0, v164
	s_waitcnt lgkmcnt(3)
	v_mov_b32_e32 v165, v172
	v_mov_b32_e32 v172, v169
	v_log_f32_e32 v181, v164
	v_mov_b32_e32 v164, v168
	v_pk_mul_f32 v[168:169], v[146:147], v[172:173]
	s_nop 0
	v_pk_fma_f32 v[164:165], v[148:149], v[164:165], v[168:169]
	v_mov_b32_e32 v168, v170
	v_mov_b32_e32 v169, v174
	v_pk_fma_f32 v[164:165], v[144:145], v[168:169], v[164:165]
	v_mov_b32_e32 v174, v171
	v_pk_fma_f32 v[164:165], v[142:143], v[174:175], v[164:165]
	s_nop 0
	v_add_f32_e32 v164, v162, v164
	v_add_f32_e32 v170, v164, v165
	s_waitcnt lgkmcnt(1)
	v_mov_b32_e32 v165, v188
	v_mov_b32_e32 v188, v177
	v_mov_b32_e32 v164, v176
	v_pk_mul_f32 v[168:169], v[140:141], v[188:189]
	s_nop 0
	v_pk_fma_f32 v[164:165], v[138:139], v[164:165], v[168:169]
	v_mov_b32_e32 v168, v178
	v_mov_b32_e32 v169, v190
	v_pk_fma_f32 v[164:165], v[136:137], v[168:169], v[164:165]
	v_mov_b32_e32 v190, v179
	v_pk_fma_f32 v[164:165], v[134:135], v[190:191], v[164:165]
	s_nop 0
	v_add_f32_e32 v164, v170, v164
	v_add_f32_e32 v164, v164, v165
	v_mul_f32_e32 v165, 0x3f317218, v181
	v_max_f32_e32 v164, 0xc2a00000, v164
	v_fmac_f32_e32 v150, 0xbd800000, v165
	v_lshl_add_u32 v165, v81, 6, s2
	v_mul_f32_e32 v164, 0xbfb8aa3b, v164
	ds_read_b128 v[168:171], v165
	ds_read_b128 v[172:175], v165 offset:16
	v_exp_f32_e32 v164, v164
	ds_read_b128 v[176:179], v165 offset:32
	ds_read_b128 v[188:191], v165 offset:48
	s_movk_i32 s2, 0x100
	v_cmp_gt_u32_e32 vcc, s2, v0
	v_add_f32_e32 v164, 1.0, v164
	s_waitcnt lgkmcnt(2)
	v_mov_b32_e32 v165, v172
	v_mov_b32_e32 v172, v169
	v_log_f32_e32 v180, v164
	v_mov_b32_e32 v164, v168
	v_pk_mul_f32 v[146:147], v[146:147], v[172:173]
	s_nop 0
	v_pk_fma_f32 v[146:147], v[148:149], v[164:165], v[146:147]
	v_mov_b32_e32 v148, v170
	v_mov_b32_e32 v149, v174
	v_pk_fma_f32 v[144:145], v[144:145], v[148:149], v[146:147]
	v_mov_b32_e32 v174, v171
	v_pk_fma_f32 v[142:143], v[142:143], v[174:175], v[144:145]
	s_nop 0
	v_add_f32_e32 v142, v162, v142
	v_add_f32_e32 v144, v142, v143
	s_waitcnt lgkmcnt(0)
	v_mov_b32_e32 v143, v188
	v_mov_b32_e32 v188, v177
	v_mov_b32_e32 v142, v176
	v_pk_mul_f32 v[140:141], v[140:141], v[188:189]
	s_nop 0
	v_pk_fma_f32 v[138:139], v[138:139], v[142:143], v[140:141]
	v_mov_b32_e32 v140, v178
	v_mov_b32_e32 v141, v190
	v_pk_fma_f32 v[136:137], v[136:137], v[140:141], v[138:139]
	v_mov_b32_e32 v190, v179
	v_pk_fma_f32 v[134:135], v[134:135], v[190:191], v[136:137]
	s_nop 0
	v_add_f32_e32 v134, v144, v134
	v_add_f32_e32 v134, v134, v135
	v_max_f32_e32 v134, 0xc2a00000, v134
	v_mul_f32_e32 v134, 0xbfb8aa3b, v134
	v_exp_f32_e32 v134, v134
	v_lshl_add_u32 v135, v167, 10, v78
	ds_write_b32 v135, v150
	v_mul_f32_e32 v135, 0x3f317218, v180
	v_add_f32_e32 v134, 1.0, v134
	v_log_f32_e32 v134, v134
	v_fmac_f32_e32 v150, 0xbd800000, v135
	v_lshl_add_u32 v135, v163, 10, v78
	ds_write_b32 v135, v150
	v_mul_f32_e32 v134, 0x3f317218, v134
	v_fmac_f32_e32 v150, 0xbd800000, v134
	v_lshl_add_u32 v78, v81, 10, v78
	ds_write_b32 v78, v150
	s_and_saveexec_b64 s[2:3], vcc
	v_lshl_add_u32 v78, v161, 2, 0
	v_add_u32_e32 v78, 0x24000, v78
	ds_write_b32 v78, v150
	s_or_b64 exec, exec, s[2:3]
	v_lshl_add_u32 v78, v185, 5, 0
	v_lshl_add_u32 v138, v160, 10, v78
	s_waitcnt lgkmcnt(0)
	s_barrier
	ds_read_b128 v[134:137], v138
	ds_read_b128 v[138:141], v138 offset:16
	s_add_i32 s3, 0, 0x11000
	s_mov_b32 s2, 0x3e000000
	s_waitcnt vmcnt(31)
	v_lshlrev_b32_e32 v162, 16, v74
	s_waitcnt lgkmcnt(1)
	v_mul_f32_e32 v142, 0x3fb8aa3b, v134
	s_waitcnt lgkmcnt(0)
	v_mul_f32_e32 v143, 0x3fb8aa3b, v138
	v_exp_f32_e32 v144, v143
	v_mul_f32_e32 v143, 0x3fb8aa3b, v135
	v_exp_f32_e32 v142, v142
	v_exp_f32_e32 v143, v143
	v_mul_f32_e32 v147, 0x3fb8aa3b, v140
	v_mul_f32_e32 v146, 0x3fb8aa3b, v136
	v_exp_f32_e32 v148, v147
	v_mul_f32_e32 v147, 0x3fb8aa3b, v137
	v_exp_f32_e32 v146, v146
	v_exp_f32_e32 v147, v147
	v_mul_f32_e32 v145, 0x3fb8aa3b, v139
	v_exp_f32_e32 v145, v145
	v_pk_mul_f32 v[142:143], v[142:143], s[2:3] op_sel_hi:[1,0]
	v_and_b32_e32 v163, 0xffff0000, v74
	v_mul_f32_e32 v149, 0x3fb8aa3b, v141
	v_pk_mul_f32 v[142:143], v[142:143], v[162:163]
	v_exp_f32_e32 v149, v149
	v_cvt_pk_bf16_f32 v74, v142, v143
	v_pk_mul_f32 v[142:143], v[146:147], s[2:3] op_sel_hi:[1,0]
	v_lshlrev_b32_e32 v146, 16, v75
	v_and_b32_e32 v147, 0xffff0000, v75
	v_pk_mul_f32 v[142:143], v[142:143], v[146:147]
	v_mul_f32_e32 v134, 0xbfb8aa3b, v134
	v_mul_f32_e32 v135, 0xbfb8aa3b, v135
	v_cvt_pk_bf16_f32 v75, v142, v143
	v_pk_mul_f32 v[142:143], v[144:145], s[2:3] op_sel_hi:[1,0]
	v_lshlrev_b32_e32 v144, 16, v76
	v_and_b32_e32 v145, 0xffff0000, v76
	v_exp_f32_e32 v134, v134
	v_exp_f32_e32 v135, v135
	v_pk_mul_f32 v[142:143], v[142:143], v[144:145]
	v_mul_f32_e32 v136, 0xbfb8aa3b, v136
	v_mul_f32_e32 v137, 0xbfb8aa3b, v137
	v_cvt_pk_bf16_f32 v76, v142, v143
	v_pk_mul_f32 v[142:143], v[148:149], s[2:3] op_sel_hi:[1,0]
	v_lshlrev_b32_e32 v144, 16, v77
	v_and_b32_e32 v145, 0xffff0000, v77
	v_exp_f32_e32 v136, v136
	v_exp_f32_e32 v137, v137
	v_pk_mul_f32 v[142:143], v[142:143], v[144:145]
	v_mul_f32_e32 v138, 0xbfb8aa3b, v138
	v_mul_f32_e32 v139, 0xbfb8aa3b, v139
	v_cvt_pk_bf16_f32 v77, v142, v143
	s_waitcnt vmcnt(30)
	v_lshlrev_b32_e32 v142, 16, v70
	v_and_b32_e32 v143, 0xffff0000, v70
	v_exp_f32_e32 v138, v138
	v_exp_f32_e32 v139, v139
	v_pk_mul_f32 v[134:135], v[134:135], v[142:143]
	v_mul_f32_e32 v140, 0xbfb8aa3b, v140
	v_mul_f32_e32 v141, 0xbfb8aa3b, v141
	v_cvt_pk_bf16_f32 v70, v134, v135
	v_lshlrev_b32_e32 v134, 16, v71
	v_and_b32_e32 v135, 0xffff0000, v71
	v_exp_f32_e32 v140, v140
	v_exp_f32_e32 v141, v141
	v_pk_mul_f32 v[134:135], v[136:137], v[134:135]
	v_lshlrev_b32_e32 v81, 4, v185
	v_cvt_pk_bf16_f32 v71, v134, v135
	v_lshlrev_b32_e32 v134, 16, v72
	v_and_b32_e32 v135, 0xffff0000, v72
	v_pk_mul_f32 v[134:135], v[138:139], v[134:135]
	v_add_u32_e32 v150, s3, v81
	s_add_i32 s13, 0, 0x1a000
	v_cvt_pk_bf16_f32 v72, v134, v135
	v_lshlrev_b32_e32 v134, 16, v73
	v_and_b32_e32 v135, 0xffff0000, v73
	s_movk_i32 s8, 0x240
	v_add_u32_e32 v81, s13, v81
	v_pk_mul_f32 v[134:135], v[140:141], v[134:135]
	v_mad_u32_u24 v138, v160, s8, v150
	v_lshl_add_u32 v139, v159, 10, v78
	v_cvt_pk_bf16_f32 v73, v134, v135
	ds_read_b128 v[134:137], v139
	ds_write_b128 v138, v[74:77]
	v_mad_u32_u24 v74, v160, s8, v81
	ds_write_b128 v74, v[70:73]
	ds_read_b128 v[70:73], v139 offset:16
	s_waitcnt lgkmcnt(3)
	v_mul_f32_e32 v75, 0xbfb8aa3b, v134
	v_exp_f32_e32 v76, v75
	v_mul_f32_e32 v74, 0x3fb8aa3b, v134
	v_exp_f32_e32 v74, v74
	s_waitcnt lgkmcnt(0)
	v_mul_f32_e32 v75, 0x3fb8aa3b, v70
	v_exp_f32_e32 v134, v75
	v_mul_f32_e32 v75, 0x3fb8aa3b, v135
	v_exp_f32_e32 v75, v75
	v_mul_f32_e32 v139, 0x3fb8aa3b, v72
	v_mul_f32_e32 v138, 0x3fb8aa3b, v136
	v_exp_f32_e32 v140, v139
	v_mul_f32_e32 v139, 0x3fb8aa3b, v137
	v_exp_f32_e32 v138, v138
	v_exp_f32_e32 v139, v139
	v_mul_f32_e32 v77, 0xbfb8aa3b, v135
	v_mul_f32_e32 v135, 0x3fb8aa3b, v71
	v_exp_f32_e32 v135, v135
	v_pk_mul_f32 v[74:75], v[74:75], s[2:3] op_sel_hi:[1,0]
	s_waitcnt vmcnt(29)
	v_lshlrev_b32_e32 v142, 16, v66
	v_and_b32_e32 v143, 0xffff0000, v66
	v_mul_f32_e32 v141, 0x3fb8aa3b, v73
	v_pk_mul_f32 v[74:75], v[74:75], v[142:143]
	v_exp_f32_e32 v141, v141
	v_cvt_pk_bf16_f32 v66, v74, v75
	v_pk_mul_f32 v[74:75], v[138:139], s[2:3] op_sel_hi:[1,0]
	v_lshlrev_b32_e32 v138, 16, v67
	v_and_b32_e32 v139, 0xffff0000, v67
	v_pk_mul_f32 v[74:75], v[74:75], v[138:139]
	v_exp_f32_e32 v77, v77
	v_cvt_pk_bf16_f32 v67, v74, v75
	v_pk_mul_f32 v[74:75], v[134:135], s[2:3] op_sel_hi:[1,0]
	v_lshlrev_b32_e32 v134, 16, v68
	v_and_b32_e32 v135, 0xffff0000, v68
	v_pk_mul_f32 v[74:75], v[74:75], v[134:135]
	v_mul_f32_e32 v136, 0xbfb8aa3b, v136
	v_mul_f32_e32 v137, 0xbfb8aa3b, v137
	v_cvt_pk_bf16_f32 v68, v74, v75
	v_pk_mul_f32 v[74:75], v[140:141], s[2:3] op_sel_hi:[1,0]
	v_lshlrev_b32_e32 v134, 16, v69
	v_and_b32_e32 v135, 0xffff0000, v69
	v_exp_f32_e32 v136, v136
	v_exp_f32_e32 v137, v137
	v_pk_mul_f32 v[74:75], v[74:75], v[134:135]
	v_mul_f32_e32 v70, 0xbfb8aa3b, v70
	v_mul_f32_e32 v71, 0xbfb8aa3b, v71
	v_cvt_pk_bf16_f32 v69, v74, v75
	s_waitcnt vmcnt(28)
	v_lshlrev_b32_e32 v74, 16, v62
	v_and_b32_e32 v75, 0xffff0000, v62
	v_exp_f32_e32 v70, v70
	v_exp_f32_e32 v71, v71
	v_pk_mul_f32 v[74:75], v[76:77], v[74:75]
	v_mul_f32_e32 v72, 0xbfb8aa3b, v72
	v_mul_f32_e32 v73, 0xbfb8aa3b, v73
	v_cvt_pk_bf16_f32 v62, v74, v75
	v_lshlrev_b32_e32 v74, 16, v63
	v_and_b32_e32 v75, 0xffff0000, v63
	v_exp_f32_e32 v72, v72
	v_exp_f32_e32 v73, v73
	v_pk_mul_f32 v[74:75], v[136:137], v[74:75]
	v_add_u32_e32 v161, 0x24000, v78
	v_cvt_pk_bf16_f32 v63, v74, v75
	v_lshlrev_b32_e32 v74, 16, v64
	v_and_b32_e32 v75, 0xffff0000, v64
	v_pk_mul_f32 v[70:71], v[70:71], v[74:75]
	s_waitcnt vmcnt(27)
	v_lshlrev_b32_e32 v142, 16, v58
	v_cvt_pk_bf16_f32 v64, v70, v71
	v_lshlrev_b32_e32 v70, 16, v65
	v_and_b32_e32 v71, 0xffff0000, v65
	v_pk_mul_f32 v[70:71], v[72:73], v[70:71]
	v_and_b32_e32 v143, 0xffff0000, v58
	v_cvt_pk_bf16_f32 v65, v70, v71
	v_mad_u32_u24 v70, v159, s8, v150
	ds_write_b128 v70, v[66:69]
	v_mad_u32_u24 v66, v159, s8, v81
	ds_write_b128 v66, v[62:65]
	v_lshl_add_u32 v70, v158, 10, v78
	ds_read_b128 v[62:65], v161 offset:16
	ds_read_b128 v[66:69], v70 offset:16
	ds_read_b128 v[70:73], v70
	ds_read_b128 v[74:77], v161
	v_readlane_b32 s11, v254, 21
	s_lshr_b32 s5, s11, 1
	s_waitcnt lgkmcnt(2)
	v_pk_add_f32 v[66:67], v[66:67], v[62:63]
	v_pk_add_f32 v[68:69], v[68:69], v[64:65]
	s_waitcnt lgkmcnt(0)
	v_pk_add_f32 v[70:71], v[70:71], v[74:75]
	v_mul_f32_e32 v135, 0x3fb8aa3b, v66
	v_mul_f32_e32 v134, 0x3fb8aa3b, v70
	v_exp_f32_e32 v136, v135
	v_mul_f32_e32 v135, 0x3fb8aa3b, v71
	v_pk_add_f32 v[72:73], v[72:73], v[76:77]
	v_exp_f32_e32 v134, v134
	v_exp_f32_e32 v135, v135
	v_mul_f32_e32 v139, 0x3fb8aa3b, v68
	v_mul_f32_e32 v138, 0x3fb8aa3b, v72
	v_exp_f32_e32 v140, v139
	v_mul_f32_e32 v139, 0x3fb8aa3b, v73
	v_exp_f32_e32 v138, v138
	v_exp_f32_e32 v139, v139
	v_mul_f32_e32 v137, 0x3fb8aa3b, v67
	v_exp_f32_e32 v137, v137
	v_pk_mul_f32 v[134:135], v[134:135], s[2:3] op_sel_hi:[1,0]
	v_mul_f32_e32 v141, 0x3fb8aa3b, v69
	v_pk_mul_f32 v[134:135], v[134:135], v[142:143]
	v_exp_f32_e32 v141, v141
	v_cvt_pk_bf16_f32 v58, v134, v135
	v_pk_mul_f32 v[134:135], v[138:139], s[2:3] op_sel_hi:[1,0]
	v_lshlrev_b32_e32 v138, 16, v59
	v_and_b32_e32 v139, 0xffff0000, v59
	v_pk_mul_f32 v[134:135], v[134:135], v[138:139]
	v_mul_f32_e32 v70, 0xbfb8aa3b, v70
	v_mul_f32_e32 v71, 0xbfb8aa3b, v71
	v_cvt_pk_bf16_f32 v59, v134, v135
	v_pk_mul_f32 v[134:135], v[136:137], s[2:3] op_sel_hi:[1,0]
	v_lshlrev_b32_e32 v136, 16, v60
	v_and_b32_e32 v137, 0xffff0000, v60
	v_exp_f32_e32 v70, v70
	v_exp_f32_e32 v71, v71
	v_pk_mul_f32 v[134:135], v[134:135], v[136:137]
	v_mul_f32_e32 v72, 0xbfb8aa3b, v72
	v_mul_f32_e32 v73, 0xbfb8aa3b, v73
	v_cvt_pk_bf16_f32 v60, v134, v135
	v_pk_mul_f32 v[134:135], v[140:141], s[2:3] op_sel_hi:[1,0]
	v_lshlrev_b32_e32 v136, 16, v61
	v_and_b32_e32 v137, 0xffff0000, v61
	v_exp_f32_e32 v72, v72
	v_exp_f32_e32 v73, v73
	v_pk_mul_f32 v[134:135], v[134:135], v[136:137]
	v_mul_f32_e32 v66, 0xbfb8aa3b, v66
	v_mul_f32_e32 v67, 0xbfb8aa3b, v67
	v_cvt_pk_bf16_f32 v61, v134, v135
	s_waitcnt vmcnt(26)
	v_lshlrev_b32_e32 v134, 16, v54
	v_and_b32_e32 v135, 0xffff0000, v54
	v_exp_f32_e32 v66, v66
	v_exp_f32_e32 v67, v67
	v_pk_mul_f32 v[70:71], v[70:71], v[134:135]
	v_mul_f32_e32 v68, 0xbfb8aa3b, v68
	v_mul_f32_e32 v69, 0xbfb8aa3b, v69
	v_cvt_pk_bf16_f32 v54, v70, v71
	v_lshlrev_b32_e32 v70, 16, v55
	v_and_b32_e32 v71, 0xffff0000, v55
	v_exp_f32_e32 v68, v68
	v_exp_f32_e32 v69, v69
	v_pk_mul_f32 v[70:71], v[72:73], v[70:71]
	s_and_b32 s9, s5, 32
	v_cvt_pk_bf16_f32 v55, v70, v71
	v_lshlrev_b32_e32 v70, 16, v56
	v_and_b32_e32 v71, 0xffff0000, v56
	v_pk_mul_f32 v[66:67], v[66:67], v[70:71]
	s_waitcnt vmcnt(25)
	v_lshlrev_b32_e32 v70, 16, v50
	v_cvt_pk_bf16_f32 v56, v66, v67
	v_lshlrev_b32_e32 v66, 16, v57
	v_and_b32_e32 v67, 0xffff0000, v57
	v_pk_mul_f32 v[66:67], v[68:69], v[66:67]
	v_and_b32_e32 v71, 0xffff0000, v50
	v_cvt_pk_bf16_f32 v57, v66, v67
	v_mad_u32_u24 v66, v158, s8, v150
	ds_write_b128 v66, v[58:61]
	v_mad_u32_u24 v58, v158, s8, v81
	ds_write_b128 v58, v[54:57]
	v_lshl_add_u32 v58, v151, 10, v78
	ds_read_b128 v[54:57], v58
	ds_read_b128 v[58:61], v58 offset:16
	v_lshrrev_b32_e32 v183, 4, v1
	s_or_b32 s4, s4, s9
	s_and_b32 s6, s11, 0xffffff80
	s_waitcnt lgkmcnt(1)
	v_pk_add_f32 v[54:55], v[74:75], v[54:55]
	s_waitcnt lgkmcnt(0)
	v_pk_add_f32 v[58:59], v[62:63], v[58:59]
	v_pk_add_f32 v[60:61], v[64:65], v[60:61]
	v_mul_f32_e32 v63, 0x3fb8aa3b, v58
	v_mul_f32_e32 v62, 0x3fb8aa3b, v54
	v_exp_f32_e32 v64, v63
	v_mul_f32_e32 v63, 0x3fb8aa3b, v55
	v_pk_add_f32 v[56:57], v[76:77], v[56:57]
	v_exp_f32_e32 v62, v62
	v_exp_f32_e32 v63, v63
	v_mul_f32_e32 v67, 0x3fb8aa3b, v60
	v_mul_f32_e32 v66, 0x3fb8aa3b, v56
	v_exp_f32_e32 v68, v67
	v_mul_f32_e32 v67, 0x3fb8aa3b, v57
	v_exp_f32_e32 v66, v66
	v_exp_f32_e32 v67, v67
	v_mul_f32_e32 v65, 0x3fb8aa3b, v59
	v_exp_f32_e32 v65, v65
	v_pk_mul_f32 v[62:63], v[62:63], s[2:3] op_sel_hi:[1,0]
	v_mul_f32_e32 v69, 0x3fb8aa3b, v61
	v_pk_mul_f32 v[62:63], v[62:63], v[70:71]
	v_exp_f32_e32 v69, v69
	v_cvt_pk_bf16_f32 v50, v62, v63
	v_pk_mul_f32 v[62:63], v[66:67], s[2:3] op_sel_hi:[1,0]
	v_lshlrev_b32_e32 v66, 16, v51
	v_and_b32_e32 v67, 0xffff0000, v51
	v_pk_mul_f32 v[62:63], v[62:63], v[66:67]
	v_mul_f32_e32 v54, 0xbfb8aa3b, v54
	v_mul_f32_e32 v55, 0xbfb8aa3b, v55
	v_cvt_pk_bf16_f32 v51, v62, v63
	v_pk_mul_f32 v[62:63], v[64:65], s[2:3] op_sel_hi:[1,0]
	v_lshlrev_b32_e32 v64, 16, v52
	v_and_b32_e32 v65, 0xffff0000, v52
	v_exp_f32_e32 v54, v54
	v_exp_f32_e32 v55, v55
	v_pk_mul_f32 v[62:63], v[62:63], v[64:65]
	v_mul_f32_e32 v56, 0xbfb8aa3b, v56
	v_mul_f32_e32 v57, 0xbfb8aa3b, v57
	v_cvt_pk_bf16_f32 v52, v62, v63
	v_pk_mul_f32 v[62:63], v[68:69], s[2:3] op_sel_hi:[1,0]
	v_lshlrev_b32_e32 v64, 16, v53
	v_and_b32_e32 v65, 0xffff0000, v53
	v_exp_f32_e32 v56, v56
	v_exp_f32_e32 v57, v57
	v_pk_mul_f32 v[62:63], v[62:63], v[64:65]
	v_mul_f32_e32 v58, 0xbfb8aa3b, v58
	v_mul_f32_e32 v59, 0xbfb8aa3b, v59
	v_cvt_pk_bf16_f32 v53, v62, v63
	s_waitcnt vmcnt(24)
	v_lshlrev_b32_e32 v62, 16, v10
	v_and_b32_e32 v63, 0xffff0000, v10
	v_exp_f32_e32 v58, v58
	v_exp_f32_e32 v59, v59
	v_pk_mul_f32 v[54:55], v[54:55], v[62:63]
	v_mul_f32_e32 v60, 0xbfb8aa3b, v60
	v_mul_f32_e32 v61, 0xbfb8aa3b, v61
	v_cvt_pk_bf16_f32 v10, v54, v55
	v_lshlrev_b32_e32 v54, 16, v11
	v_and_b32_e32 v55, 0xffff0000, v11
	v_exp_f32_e32 v60, v60
	v_exp_f32_e32 v61, v61
	v_pk_mul_f32 v[54:55], v[56:57], v[54:55]
	s_movk_i32 s2, 0x440
	v_cvt_pk_bf16_f32 v11, v54, v55
	v_lshlrev_b32_e32 v54, 16, v12
	v_and_b32_e32 v55, 0xffff0000, v12
	v_pk_mul_f32 v[54:55], v[58:59], v[54:55]
	v_or_b32_e32 v198, s4, v183
	v_cvt_pk_bf16_f32 v12, v54, v55
	v_lshlrev_b32_e32 v54, 16, v13
	v_and_b32_e32 v55, 0xffff0000, v13
	v_pk_mul_f32 v[54:55], v[60:61], v[54:55]
	s_ashr_i32 s7, s6, 31
	v_cvt_pk_bf16_f32 v13, v54, v55
	v_mad_u32_u24 v54, v151, s8, v150
	ds_write_b128 v54, v[50:53]
	v_mad_u32_u24 v50, v151, s8, v81
	ds_write_b128 v50, v[10:13]
	v_add_u32_e32 v10, 0, v80
	v_mad_u32_u24 v11, v152, s2, v10
	s_waitcnt lgkmcnt(0)
	s_barrier
	s_waitcnt vmcnt(23)
	ds_write_b128 v11, v[6:9]
	v_mad_u32_u24 v6, v153, s2, v10
	s_waitcnt vmcnt(22)
	ds_write_b128 v6, v[2:5]
	v_mad_u32_u24 v2, v154, s2, v10
	s_waitcnt vmcnt(21)
	ds_write_b128 v2, v[30:33]
	v_mad_u32_u24 v2, v155, s2, v10
	s_waitcnt vmcnt(20)
	ds_write_b128 v2, v[14:17]
	s_waitcnt vmcnt(19)
	ds_write_b128 v11, v[38:41] offset:34816
	v_mad_u32_u24 v2, v156, s2, v10
	s_waitcnt vmcnt(18)
	ds_write_b128 v2, v[34:37]
	s_waitcnt vmcnt(17)
	ds_write_b128 v11, v[46:49] offset:52224
	v_mad_u32_u24 v2, v157, s2, v10
	s_waitcnt vmcnt(16)
	ds_write_b128 v2, v[42:45]
	v_mov_b64_e32 v[2:3], s[0:1]
	v_and_b32_e32 v191, 15, v0
	v_mad_i64_i32 v[4:5], s[0:1], v198, s12, v[2:3]
	s_lshl_b64 s[4:5], s[6:7], 1
	v_or_b32_e32 v196, 4, v198
	v_lshl_add_u64 v[4:5], v[4:5], 0, s[4:5]
	v_lshlrev_b32_e32 v78, 4, v191
	v_mad_i64_i32 v[6:7], s[0:1], v196, s12, v[2:3]
	v_lshl_add_u64 v[4:5], v[4:5], 0, v[78:79]
	v_lshl_add_u64 v[6:7], v[6:7], 0, s[4:5]
	v_or_b32_e32 v194, 8, v198
	s_waitcnt lgkmcnt(0)
	s_barrier
	v_lshl_add_u64 v[6:7], v[6:7], 0, v[78:79]
	global_load_dwordx4 v[162:165], v[4:5], off offset:2048
	global_load_dwordx4 v[158:161], v[6:7], off offset:2048
	v_mad_i64_i32 v[4:5], s[0:1], v194, s12, v[2:3]
	v_or_b32_e32 v192, 12, v198
	v_lshl_add_u64 v[4:5], v[4:5], 0, s[4:5]
	v_mad_i64_i32 v[6:7], s[0:1], v192, s12, v[2:3]
	v_lshl_add_u64 v[4:5], v[4:5], 0, v[78:79]
	v_lshl_add_u64 v[6:7], v[6:7], 0, s[4:5]
	v_or_b32_e32 v190, 16, v198
	v_lshl_add_u64 v[6:7], v[6:7], 0, v[78:79]
	global_load_dwordx4 v[154:157], v[4:5], off offset:2048
	global_load_dwordx4 v[150:153], v[6:7], off offset:2048
	v_mad_i64_i32 v[4:5], s[0:1], v190, s12, v[2:3]
	v_or_b32_e32 v188, 20, v198
	v_lshl_add_u64 v[4:5], v[4:5], 0, s[4:5]
	v_mad_i64_i32 v[6:7], s[0:1], v188, s12, v[2:3]
	v_lshl_add_u64 v[4:5], v[4:5], 0, v[78:79]
	v_lshl_add_u64 v[6:7], v[6:7], 0, s[4:5]
	v_or_b32_e32 v186, 24, v198
	v_lshl_add_u64 v[6:7], v[6:7], 0, v[78:79]
	global_load_dwordx4 v[146:149], v[4:5], off offset:2048
	global_load_dwordx4 v[142:145], v[6:7], off offset:2048
	v_mad_i64_i32 v[4:5], s[0:1], v186, s12, v[2:3]
	v_or_b32_e32 v184, 28, v198
	v_lshl_add_u64 v[4:5], v[4:5], 0, s[4:5]
	v_mad_i64_i32 v[2:3], s[0:1], v184, s12, v[2:3]
	v_lshl_add_u64 v[4:5], v[4:5], 0, v[78:79]
	v_lshl_add_u64 v[2:3], v[2:3], 0, s[4:5]
	v_lshl_add_u64 v[2:3], v[2:3], 0, v[78:79]
	global_load_dwordx4 v[138:141], v[4:5], off offset:2048
	global_load_dwordx4 v[134:137], v[2:3], off offset:2048
	s_add_i32 s13, s13, s6
	v_add_u32_e32 v2, s13, v182
	v_mad_u32_u24 v12, v185, s8, v2
	ds_read_b128 v[4:7], v12
	v_or_b32_e32 v3, s9, v185
	v_mul_u32_u24_e32 v3, 0x240, v3
	s_add_i32 s0, s6, s3
	v_add3_u32 v3, s0, v3, v182
	ds_read_b128 v[174:177], v3
	ds_read_b128 v[170:173], v3 offset:32
	ds_read_b128 v[8:11], v12 offset:32
	v_lshlrev_b32_e32 v193, 2, v166
	s_bitcmp1_b32 s11, 6
	s_cselect_b64 s[12:13], -1, 0
	s_waitcnt lgkmcnt(2)
	v_mfma_f32_32x32x16_bf16 v[66:81], v[4:7], v[174:177], 0
	ds_read_b128 v[4:7], v12 offset:64
	ds_read_b128 v[178:181], v3 offset:64
	v_cmp_le_u32_e64 s[0:1], v193, v185
	v_cmp_lt_u32_e64 s[2:3], v193, v185
	v_or_b32_e32 v40, 2, v193
	v_or_b32_e32 v41, 3, v193
	v_or_b32_e32 v37, 8, v193
	s_waitcnt lgkmcnt(2)
	v_mfma_f32_32x32x16_bf16 v[66:81], v[8:11], v[170:173], v[66:81]
	ds_read_b128 v[166:169], v3 offset:96
	ds_read_b128 v[8:11], v12 offset:96
	v_or_b32_e32 v43, 9, v193
	v_or_b32_e32 v42, 10, v193
	v_or_b32_e32 v38, 11, v193
	v_or_b32_e32 v35, 16, v193
	v_or_b32_e32 v33, 17, v193
	s_and_b64 vcc, exec, s[12:13]
	s_waitcnt lgkmcnt(2)
	v_mfma_f32_32x32x16_bf16 v[66:81], v[4:7], v[178:181], v[66:81]
	v_or_b32_e32 v39, 18, v193
	v_or_b32_e32 v36, 19, v193
	v_or_b32_e32 v34, 24, v193
	v_or_b32_e32 v32, 25, v193
	v_or_b32_e32 v31, 26, v193
	v_or_b32_e32 v30, 27, v193
	s_waitcnt lgkmcnt(0)
	v_mfma_f32_32x32x16_bf16 v[66:81], v[8:11], v[166:169], v[66:81]
	s_cbranch_vccnz .LBB0_471
	v_cmp_le_u32_e32 vcc, v40, v185
	s_nop 9
	v_cndmask_b32_e64 v67, 0, v67, s[2:3]
	v_cndmask_b32_e64 v66, 0, v66, s[0:1]
	v_cndmask_b32_e32 v68, 0, v68, vcc
	v_cmp_le_u32_e32 vcc, v41, v185
	s_nop 1
	v_cndmask_b32_e32 v69, 0, v69, vcc
	v_cmp_le_u32_e32 vcc, v37, v185
	s_nop 1
	v_cndmask_b32_e32 v70, 0, v70, vcc
	v_cmp_le_u32_e32 vcc, v43, v185
	s_nop 1
	v_cndmask_b32_e32 v71, 0, v71, vcc
	v_cmp_le_u32_e32 vcc, v42, v185
	s_nop 1
	v_cndmask_b32_e32 v72, 0, v72, vcc
	v_cmp_le_u32_e32 vcc, v38, v185
	s_nop 1
	v_cndmask_b32_e32 v73, 0, v73, vcc
	v_cmp_le_u32_e32 vcc, v35, v185
	s_nop 1
	v_cndmask_b32_e32 v74, 0, v74, vcc
	v_cmp_le_u32_e32 vcc, v33, v185
	s_nop 1
	v_cndmask_b32_e32 v75, 0, v75, vcc
	v_cmp_le_u32_e32 vcc, v39, v185
	s_nop 1
	v_cndmask_b32_e32 v76, 0, v76, vcc
	v_cmp_le_u32_e32 vcc, v36, v185
	s_nop 1
	v_cndmask_b32_e32 v77, 0, v77, vcc
	v_cmp_le_u32_e32 vcc, v34, v185
	s_nop 1
	v_cndmask_b32_e32 v78, 0, v78, vcc
	v_cmp_le_u32_e32 vcc, v32, v185
	s_nop 1
	v_cndmask_b32_e32 v79, 0, v79, vcc
	v_cmp_le_u32_e32 vcc, v31, v185
	s_nop 1
	v_cndmask_b32_e32 v80, 0, v80, vcc
	v_cmp_le_u32_e32 vcc, v30, v185
	s_nop 1
	v_cndmask_b32_e32 v81, 0, v81, vcc
